# K-loop LDS-DMA issued in saddr form (SGPR base + 32-bit lane offset), dead 64-bit address VALU removed; on top of v057
# speedup vs baseline: 1.0152x; 1.0045x over previous
; #define PG8_STAGE(bufoff, gbase, voff) do { _Pragma("unroll") for (int _i = 0; _i < 2; ++_i) \
;         __builtin_amdgcn_global_load_lds((const unsigned*)((const char*)(gbase) + (voff)[_i]), (PG8_LAS unsigned*)(lds + (bufoff) + ldsw + _i * 8192), 16, 0, 0); } while (0)
; #define PG8_LDA(dst, b, h) do { _Pragma("unroll") for (int m = 0; m < 4; ++m) _Pragma("unroll") for (int k = 0; k < 2; ++k) dst[m][k] = *(const PG8_LAS bf16x8*)(lds + PG8_SA(b, h) + aoff + m * 2048 + k * 1024); } while (0)
; #define PG8_LDB(dst, b, h) do { _Pragma("unroll") for (int n = 0; n < 2; ++n) _Pragma("unroll") for (int k = 0; k < 2; ++k) dst[n][k] = *(const PG8_LAS bf16x8*)(lds + PG8_SB(b, h) + boff + n * 2048 + k * 1024); } while (0)
; #define PG8_MMA(ai, bj, At, Bt) do { __builtin_amdgcn_s_setprio(1); _Pragma("unroll") for (int m = 0; m < 4; ++m) _Pragma("unroll") for (int n = 0; n < 2; ++n) _Pragma("unroll") for (int k = 0; k < 2; ++k) \
;         acc[ai][bj][m][n] = __builtin_amdgcn_mfma_f32_16x16x32_bf16(Bt[n][k], At[m][k], acc[ai][bj][m][n], 0, 0, 0); __builtin_amdgcn_s_setprio(0); } while (0)
; #define PG8_WAIT_V(n) asm volatile("s_waitcnt vmcnt(" #n ")" ::: "memory")
; #define PG8_BAR __builtin_amdgcn_s_barrier()
; template <class Epi, class Sched, bool ALIGN_EPI = false, bool SP2 = false>
; __device__ __forceinline__ void gemm_phase(PG8_LAS unsigned char* lds, const Gemm g, const Sched& S, const Epi& E) {
;     ...
;         for (int t = 0; t < nt; t += 2) {
;             const bool last = (t == nt - 2);
;             const char* a1 = cA + (size_t)(t + 1) * kstep;
;             const char* a2 = last ? nA : cA + (size_t)(t + 2) * kstep; const char* b2 = last ? nB : cB + (size_t)(t + 2) * kstep;
;             const char* a3 = a2 + kstep; const char* b3 = b2 + kstep;
;             if (last && has_next) S.a_ready(nxt);
;             if constexpr (SP2) {
;             PG8_LDB(B0, 0, 0); PG8_LDB(B1, 0, 1); PG8_SCHED; PG8_LDA(At, 0, 0); PG8_STAGE(PG8_SA(1, 1), a1 + hstep, voffA);
;             PG8_WAIT_V(8); PG8_WAIT_L(0); PG8_BAR; PG8_MMA(0, 0, At, B0); PG8_MMA(0, 1, At, B1); PG8_BAR; PG8_SCHED;
;             PG8_LDA(At, 0, 1); PG8_STAGE(PG8_SB(0, 0), b2, voffB); PG8_STAGE(PG8_SB(0, 1), b2 + hstep, voffB); PG8_STAGE(PG8_SA(0, 0), a2, voffA);
;             PG8_WAIT_V(8); PG8_WAIT_L(0); PG8_BAR; PG8_MMA(1, 0, At, B0); PG8_MMA(1, 1, At, B1); PG8_BAR; PG8_SCHED;
.LBB0_180:
	s_add_u32 s36, s34, 0xfff00000
	s_addc_u32 s37, s35, -1
	s_mov_b32 m0, s45
	s_nop 0
	global_load_lds_dwordx4 v138, s[36:37]
	s_mov_b32 m0, s46
	s_nop 0
	global_load_lds_dwordx4 v142, s[36:37]
	s_add_u32 s36, s36, 0x80
	s_addc_u32 s37, s37, 0
	ds_read_b128 v[130:133], v170
	ds_read_b128 v[134:137], v170 offset:1024
	ds_read_b128 v[178:181], v170 offset:2048
	ds_read_b128 v[182:185], v170 offset:3072
	ds_read_b128 v[186:189], v171
	ds_read_b128 v[190:193], v171 offset:1024
	ds_read_b128 v[194:197], v171 offset:2048
	ds_read_b128 v[200:203], v171 offset:3072
	s_cmp_eq_u32 s56, 60
	s_cselect_b32 s39, s7, s37
	s_cselect_b32 s38, s25, s36
	s_cselect_b32 s37, s15, s55
	s_cselect_b32 s36, s31, s54
	s_add_i32 m0, s40, 0xc000
	ds_read_b128 v[204:207], v172
	ds_read_b128 v[208:211], v172 offset:1024
	ds_read_b128 v[212:215], v172 offset:2048
	ds_read_b128 v[216:219], v172 offset:3072
	ds_read_b128 v[220:223], v172 offset:4096
	ds_read_b128 v[224:227], v172 offset:5120
	ds_read_b128 v[228:231], v172 offset:6144
	ds_read_b128 v[232:235], v172 offset:7168
	global_load_lds_dwordx4 v148, s[34:35]
	s_add_i32 m0, s40, 0xe000
	s_nop 0
	global_load_lds_dwordx4 v150, s[34:35]
	s_waitcnt vmcnt(8)
	s_waitcnt lgkmcnt(0)
	s_barrier
	v_mfma_f32_16x16x32_bf16 v[126:129], v[130:133], v[204:207], v[126:129]
	v_mfma_f32_16x16x32_bf16 v[122:125], v[178:181], v[204:207], v[122:125]
	v_mfma_f32_16x16x32_bf16 v[110:113], v[130:133], v[212:215], v[110:113]
	v_mfma_f32_16x16x32_bf16 v[106:109], v[178:181], v[212:215], v[106:109]
	v_mfma_f32_16x16x32_bf16 v[94:97], v[130:133], v[220:223], v[94:97]
	v_mfma_f32_16x16x32_bf16 v[90:93], v[178:181], v[220:223], v[90:93]
	v_mfma_f32_16x16x32_bf16 v[78:81], v[130:133], v[228:231], v[78:81]
	v_mfma_f32_16x16x32_bf16 v[74:77], v[178:181], v[228:231], v[74:77]
	v_mfma_f32_16x16x32_bf16 v[126:129], v[134:137], v[208:211], v[126:129]
	v_mfma_f32_16x16x32_bf16 v[122:125], v[182:185], v[208:211], v[122:125]
	v_mfma_f32_16x16x32_bf16 v[110:113], v[134:137], v[216:219], v[110:113]
	v_mfma_f32_16x16x32_bf16 v[106:109], v[182:185], v[216:219], v[106:109]
	v_mfma_f32_16x16x32_bf16 v[94:97], v[134:137], v[224:227], v[94:97]
	v_mfma_f32_16x16x32_bf16 v[90:93], v[182:185], v[224:227], v[90:93]
	v_mfma_f32_16x16x32_bf16 v[78:81], v[134:137], v[232:235], v[78:81]
	v_mfma_f32_16x16x32_bf16 v[74:77], v[182:185], v[232:235], v[74:77]
	v_mfma_f32_16x16x32_bf16 v[118:121], v[186:189], v[204:207], v[118:121]
	v_mfma_f32_16x16x32_bf16 v[114:117], v[194:197], v[204:207], v[114:117]
	v_mfma_f32_16x16x32_bf16 v[102:105], v[186:189], v[212:215], v[102:105]
	v_mfma_f32_16x16x32_bf16 v[98:101], v[194:197], v[212:215], v[98:101]
	v_mfma_f32_16x16x32_bf16 v[86:89], v[186:189], v[220:223], v[86:89]
	v_mfma_f32_16x16x32_bf16 v[82:85], v[194:197], v[220:223], v[82:85]
	v_mfma_f32_16x16x32_bf16 v[70:73], v[186:189], v[228:231], v[70:73]
	v_mfma_f32_16x16x32_bf16 v[66:69], v[194:197], v[228:231], v[66:69]
	v_mfma_f32_16x16x32_bf16 v[118:121], v[190:193], v[208:211], v[118:121]
	v_mfma_f32_16x16x32_bf16 v[114:117], v[200:203], v[208:211], v[114:117]
	v_mfma_f32_16x16x32_bf16 v[102:105], v[190:193], v[216:219], v[102:105]
	v_mfma_f32_16x16x32_bf16 v[98:101], v[200:203], v[216:219], v[98:101]
	v_mfma_f32_16x16x32_bf16 v[86:89], v[190:193], v[224:227], v[86:89]
	v_mfma_f32_16x16x32_bf16 v[82:85], v[200:203], v[224:227], v[82:85]
	v_mfma_f32_16x16x32_bf16 v[70:73], v[190:193], v[232:235], v[70:73]
	v_mfma_f32_16x16x32_bf16 v[66:69], v[200:203], v[232:235], v[66:69]
	s_barrier
	s_add_i32 s57, s49, s33
	v_lshl_add_u64 v[156:157], s[36:37], 0, v[140:141]
	s_mov_b32 m0, s57
	ds_read_b128 v[204:207], v172 offset:16384
	ds_read_b128 v[208:211], v172 offset:17408
	ds_read_b128 v[212:215], v172 offset:18432
	ds_read_b128 v[216:219], v172 offset:19456
	ds_read_b128 v[220:223], v172 offset:20480
	ds_read_b128 v[224:227], v172 offset:21504
	ds_read_b128 v[228:231], v172 offset:22528
	ds_read_b128 v[232:235], v172 offset:23552
	global_load_lds_dwordx4 v140, s[36:37]
	s_add_i32 m0, s57, 0x2000
	s_add_u32 s58, s36, 0x100000
	v_lshl_add_u64 v[236:237], s[36:37], 0, v[144:145]
	s_addc_u32 s59, s37, 0
	s_add_i32 s57, s50, s33
	global_load_lds_dwordx4 v144, s[36:37]
	s_mov_b32 m0, s57
	s_nop 0
	global_load_lds_dwordx4 v140, s[58:59]
	s_add_i32 m0, s57, 0x2000
	s_nop 0
	global_load_lds_dwordx4 v144, s[58:59]
	s_waitcnt vmcnt(6)
	s_waitcnt lgkmcnt(0)
	s_barrier
	v_mfma_f32_16x16x32_bf16 v[62:65], v[130:133], v[204:207], v[62:65]
	v_mfma_f32_16x16x32_bf16 v[58:61], v[178:181], v[204:207], v[58:61]
	v_mfma_f32_16x16x32_bf16 v[46:49], v[130:133], v[212:215], v[46:49]
	v_mfma_f32_16x16x32_bf16 v[42:45], v[178:181], v[212:215], v[42:45]
	v_mfma_f32_16x16x32_bf16 v[30:33], v[130:133], v[220:223], v[30:33]
	v_mfma_f32_16x16x32_bf16 v[26:29], v[178:181], v[220:223], v[26:29]
	v_mfma_f32_16x16x32_bf16 v[14:17], v[130:133], v[228:231], v[14:17]
	v_mfma_f32_16x16x32_bf16 v[10:13], v[178:181], v[228:231], v[10:13]
	v_mfma_f32_16x16x32_bf16 v[62:65], v[134:137], v[208:211], v[62:65]
	v_mfma_f32_16x16x32_bf16 v[58:61], v[182:185], v[208:211], v[58:61]
	v_mfma_f32_16x16x32_bf16 v[46:49], v[134:137], v[216:219], v[46:49]
	v_mfma_f32_16x16x32_bf16 v[42:45], v[182:185], v[216:219], v[42:45]
	v_mfma_f32_16x16x32_bf16 v[30:33], v[134:137], v[224:227], v[30:33]
	v_mfma_f32_16x16x32_bf16 v[26:29], v[182:185], v[224:227], v[26:29]
	v_mfma_f32_16x16x32_bf16 v[14:17], v[134:137], v[232:235], v[14:17]
	v_mfma_f32_16x16x32_bf16 v[10:13], v[182:185], v[232:235], v[10:13]
	v_mfma_f32_16x16x32_bf16 v[54:57], v[186:189], v[204:207], v[54:57]
	v_mfma_f32_16x16x32_bf16 v[50:53], v[194:197], v[204:207], v[50:53]
	v_mfma_f32_16x16x32_bf16 v[38:41], v[186:189], v[212:215], v[38:41]
	v_mfma_f32_16x16x32_bf16 v[34:37], v[194:197], v[212:215], v[34:37]
	v_mfma_f32_16x16x32_bf16 v[22:25], v[186:189], v[220:223], v[22:25]
	v_mfma_f32_16x16x32_bf16 v[18:21], v[194:197], v[220:223], v[18:21]
	v_mfma_f32_16x16x32_bf16 v[6:9], v[186:189], v[228:231], v[6:9]
	v_mfma_f32_16x16x32_bf16 v[2:5], v[194:197], v[228:231], v[2:5]
	v_mfma_f32_16x16x32_bf16 v[54:57], v[190:193], v[208:211], v[54:57]
	v_mfma_f32_16x16x32_bf16 v[50:53], v[200:203], v[208:211], v[50:53]
	v_mfma_f32_16x16x32_bf16 v[38:41], v[190:193], v[216:219], v[38:41]
	v_mfma_f32_16x16x32_bf16 v[34:37], v[200:203], v[216:219], v[34:37]
	v_mfma_f32_16x16x32_bf16 v[22:25], v[190:193], v[224:227], v[22:25]
	v_mfma_f32_16x16x32_bf16 v[18:21], v[200:203], v[224:227], v[18:21]
	v_mfma_f32_16x16x32_bf16 v[6:9], v[190:193], v[232:235], v[6:9]
	v_mfma_f32_16x16x32_bf16 v[2:5], v[200:203], v[232:235], v[2:5]
	s_barrier
; #define PG8_STAGE(bufoff, gbase, voff) do { _Pragma("unroll") for (int _i = 0; _i < 2; ++_i) \
;         __builtin_amdgcn_global_load_lds((const unsigned*)((const char*)(gbase) + (voff)[_i]), (PG8_LAS unsigned*)(lds + (bufoff) + ldsw + _i * 8192), 16, 0, 0); } while (0)
; #define PG8_LDA(dst, b, h) do { _Pragma("unroll") for (int m = 0; m < 4; ++m) _Pragma("unroll") for (int k = 0; k < 2; ++k) dst[m][k] = *(const PG8_LAS bf16x8*)(lds + PG8_SA(b, h) + aoff + m * 2048 + k * 1024); } while (0)
; #define PG8_LDB(dst, b, h) do { _Pragma("unroll") for (int n = 0; n < 2; ++n) _Pragma("unroll") for (int k = 0; k < 2; ++k) dst[n][k] = *(const PG8_LAS bf16x8*)(lds + PG8_SB(b, h) + boff + n * 2048 + k * 1024); } while (0)
; #define PG8_MMA(ai, bj, At, Bt) do { __builtin_amdgcn_s_setprio(1); _Pragma("unroll") for (int m = 0; m < 4; ++m) _Pragma("unroll") for (int n = 0; n < 2; ++n) _Pragma("unroll") for (int k = 0; k < 2; ++k) \
;         acc[ai][bj][m][n] = __builtin_amdgcn_mfma_f32_16x16x32_bf16(Bt[n][k], At[m][k], acc[ai][bj][m][n], 0, 0, 0); __builtin_amdgcn_s_setprio(0); } while (0)
; #define PG8_WAIT_V(n) asm volatile("s_waitcnt vmcnt(" #n ")" ::: "memory")
; #define PG8_WAIT_L(n) asm volatile("s_waitcnt lgkmcnt(" #n ")" ::: "memory")
; #define PG8_BAR __builtin_amdgcn_s_barrier()
; #define PG8_SCHED __builtin_amdgcn_sched_barrier(0)
; template <class Epi, class Sched, bool ALIGN_EPI = false, bool SP2 = false>
; __device__ __forceinline__ void gemm_phase(PG8_LAS unsigned char* lds, const Gemm g, const Sched& S, const Epi& E) {
;     ...
;             PG8_LDB(B0, 1, 0); PG8_LDB(B1, 1, 1); PG8_SCHED; PG8_LDA(At, 1, 0); PG8_STAGE(PG8_SA(0, 1), a2 + hstep, voffA);
;             PG8_WAIT_V(8); PG8_WAIT_L(0); PG8_BAR; PG8_MMA(0, 0, At, B0); PG8_MMA(0, 1, At, B1); PG8_BAR; PG8_SCHED;
;             PG8_LDA(At, 1, 1); PG8_STAGE(PG8_SB(1, 0), b3, voffB); PG8_STAGE(PG8_SB(1, 1), b3 + hstep, voffB); PG8_STAGE(PG8_SA(1, 0), a3, voffA);
;             PG8_WAIT_V(8); PG8_WAIT_L(0); PG8_BAR; PG8_MMA(1, 0, At, B0); PG8_MMA(1, 1, At, B1); PG8_BAR; PG8_SCHED;
	s_mov_b32 m0, s40
	s_nop 0
	global_load_lds_dwordx4 v138, s[38:39]
	s_mov_b32 m0, s41
	s_nop 0
	global_load_lds_dwordx4 v142, s[38:39]
	s_add_i32 s57, 0, 0x18000
	v_add_u32_e32 v146, s57, v159
	s_add_i32 s58, 0, 0x1c000
	ds_read_b128 v[130:133], v146
	ds_read_b128 v[134:137], v146 offset:1024
	ds_read_b128 v[178:181], v146 offset:2048
	ds_read_b128 v[182:185], v146 offset:3072
	v_add_u32_e32 v146, s58, v159
	ds_read_b128 v[186:189], v146
	ds_read_b128 v[190:193], v146 offset:1024
	ds_read_b128 v[194:197], v146 offset:2048
	ds_read_b128 v[200:203], v146 offset:3072
	s_add_u32 s38, s38, 0x100000
	s_addc_u32 s39, s39, 0
	s_mov_b32 m0, s42
	ds_read_b128 v[204:207], v172 offset:32768
	ds_read_b128 v[208:211], v172 offset:33792
	ds_read_b128 v[212:215], v172 offset:34816
	ds_read_b128 v[216:219], v172 offset:35840
	ds_read_b128 v[220:223], v172 offset:36864
	ds_read_b128 v[224:227], v172 offset:37888
	ds_read_b128 v[228:231], v172 offset:38912
	ds_read_b128 v[232:235], v172 offset:39936
	global_load_lds_dwordx4 v138, s[38:39]
	s_mov_b32 m0, s43
	s_nop 0
	global_load_lds_dwordx4 v142, s[38:39]
	s_waitcnt vmcnt(8)
	s_waitcnt lgkmcnt(0)
	s_barrier
	v_mfma_f32_16x16x32_bf16 v[126:129], v[130:133], v[204:207], v[126:129]
	v_mfma_f32_16x16x32_bf16 v[122:125], v[178:181], v[204:207], v[122:125]
	v_mfma_f32_16x16x32_bf16 v[110:113], v[130:133], v[212:215], v[110:113]
	v_mfma_f32_16x16x32_bf16 v[106:109], v[178:181], v[212:215], v[106:109]
	v_mfma_f32_16x16x32_bf16 v[94:97], v[130:133], v[220:223], v[94:97]
	v_mfma_f32_16x16x32_bf16 v[90:93], v[178:181], v[220:223], v[90:93]
	v_mfma_f32_16x16x32_bf16 v[78:81], v[130:133], v[228:231], v[78:81]
	v_mfma_f32_16x16x32_bf16 v[74:77], v[178:181], v[228:231], v[74:77]
	v_mfma_f32_16x16x32_bf16 v[126:129], v[134:137], v[208:211], v[126:129]
	v_mfma_f32_16x16x32_bf16 v[122:125], v[182:185], v[208:211], v[122:125]
	v_mfma_f32_16x16x32_bf16 v[110:113], v[134:137], v[216:219], v[110:113]
	v_mfma_f32_16x16x32_bf16 v[106:109], v[182:185], v[216:219], v[106:109]
	v_mfma_f32_16x16x32_bf16 v[94:97], v[134:137], v[224:227], v[94:97]
	v_mfma_f32_16x16x32_bf16 v[90:93], v[182:185], v[224:227], v[90:93]
	v_mfma_f32_16x16x32_bf16 v[78:81], v[134:137], v[232:235], v[78:81]
	v_mfma_f32_16x16x32_bf16 v[74:77], v[182:185], v[232:235], v[74:77]
	v_mfma_f32_16x16x32_bf16 v[118:121], v[186:189], v[204:207], v[118:121]
	v_mfma_f32_16x16x32_bf16 v[114:117], v[194:197], v[204:207], v[114:117]
	v_mfma_f32_16x16x32_bf16 v[102:105], v[186:189], v[212:215], v[102:105]
	v_mfma_f32_16x16x32_bf16 v[98:101], v[194:197], v[212:215], v[98:101]
	v_mfma_f32_16x16x32_bf16 v[86:89], v[186:189], v[220:223], v[86:89]
	v_mfma_f32_16x16x32_bf16 v[82:85], v[194:197], v[220:223], v[82:85]
	v_mfma_f32_16x16x32_bf16 v[70:73], v[186:189], v[228:231], v[70:73]
	v_mfma_f32_16x16x32_bf16 v[66:69], v[194:197], v[228:231], v[66:69]
	v_mfma_f32_16x16x32_bf16 v[118:121], v[190:193], v[208:211], v[118:121]
	v_mfma_f32_16x16x32_bf16 v[114:117], v[200:203], v[208:211], v[114:117]
	v_mfma_f32_16x16x32_bf16 v[102:105], v[190:193], v[216:219], v[102:105]
	v_mfma_f32_16x16x32_bf16 v[98:101], v[200:203], v[216:219], v[98:101]
	v_mfma_f32_16x16x32_bf16 v[86:89], v[190:193], v[224:227], v[86:89]
	v_mfma_f32_16x16x32_bf16 v[82:85], v[200:203], v[224:227], v[82:85]
	v_mfma_f32_16x16x32_bf16 v[70:73], v[190:193], v[232:235], v[70:73]
	v_mfma_f32_16x16x32_bf16 v[66:69], v[200:203], v[232:235], v[66:69]
	s_barrier
	s_add_i32 s38, s57, s33
	v_lshl_add_u64 v[156:157], v[156:157], 0, s[10:11]
	s_mov_b32 m0, s38
	ds_read_b128 v[204:207], v172 offset:49152
	ds_read_b128 v[208:211], v172 offset:50176
	ds_read_b128 v[212:215], v172 offset:51200
	ds_read_b128 v[216:219], v172 offset:52224
	ds_read_b128 v[220:223], v172 offset:53248
	ds_read_b128 v[224:227], v172 offset:54272
	ds_read_b128 v[228:231], v172 offset:55296
	ds_read_b128 v[232:235], v172 offset:56320
	global_load_lds_dwordx4 v[156:157], off
	s_add_i32 m0, s38, 0x2000
	s_add_u32 s36, s36, 0x100080
	v_lshl_add_u64 v[156:157], v[236:237], 0, s[10:11]
	s_addc_u32 s37, s37, 0
	s_add_i32 s38, s58, s33
	global_load_lds_dwordx4 v[156:157], off
	s_mov_b32 m0, s38
	s_nop 0
	global_load_lds_dwordx4 v140, s[36:37]
	s_add_i32 m0, s38, 0x2000
	s_nop 0
	global_load_lds_dwordx4 v144, s[36:37]
	s_waitcnt vmcnt(6)
	s_waitcnt lgkmcnt(0)
	s_barrier
	v_mfma_f32_16x16x32_bf16 v[62:65], v[130:133], v[204:207], v[62:65]
	v_mfma_f32_16x16x32_bf16 v[58:61], v[178:181], v[204:207], v[58:61]
	v_mfma_f32_16x16x32_bf16 v[46:49], v[130:133], v[212:215], v[46:49]
	v_mfma_f32_16x16x32_bf16 v[42:45], v[178:181], v[212:215], v[42:45]
	v_mfma_f32_16x16x32_bf16 v[30:33], v[130:133], v[220:223], v[30:33]
	v_mfma_f32_16x16x32_bf16 v[26:29], v[178:181], v[220:223], v[26:29]
	v_mfma_f32_16x16x32_bf16 v[14:17], v[130:133], v[228:231], v[14:17]
	v_mfma_f32_16x16x32_bf16 v[10:13], v[178:181], v[228:231], v[10:13]
	v_mfma_f32_16x16x32_bf16 v[62:65], v[134:137], v[208:211], v[62:65]
	v_mfma_f32_16x16x32_bf16 v[58:61], v[182:185], v[208:211], v[58:61]
	v_mfma_f32_16x16x32_bf16 v[46:49], v[134:137], v[216:219], v[46:49]
	v_mfma_f32_16x16x32_bf16 v[42:45], v[182:185], v[216:219], v[42:45]
	v_mfma_f32_16x16x32_bf16 v[30:33], v[134:137], v[224:227], v[30:33]
	v_mfma_f32_16x16x32_bf16 v[26:29], v[182:185], v[224:227], v[26:29]
	v_mfma_f32_16x16x32_bf16 v[14:17], v[134:137], v[232:235], v[14:17]
	v_mfma_f32_16x16x32_bf16 v[10:13], v[182:185], v[232:235], v[10:13]
	v_mfma_f32_16x16x32_bf16 v[54:57], v[186:189], v[204:207], v[54:57]
	v_mfma_f32_16x16x32_bf16 v[50:53], v[194:197], v[204:207], v[50:53]
	v_mfma_f32_16x16x32_bf16 v[38:41], v[186:189], v[212:215], v[38:41]
	v_mfma_f32_16x16x32_bf16 v[34:37], v[194:197], v[212:215], v[34:37]
	v_mfma_f32_16x16x32_bf16 v[22:25], v[186:189], v[220:223], v[22:25]
	v_mfma_f32_16x16x32_bf16 v[18:21], v[194:197], v[220:223], v[18:21]
	v_mfma_f32_16x16x32_bf16 v[6:9], v[186:189], v[228:231], v[6:9]
	v_mfma_f32_16x16x32_bf16 v[2:5], v[194:197], v[228:231], v[2:5]
	v_mfma_f32_16x16x32_bf16 v[54:57], v[190:193], v[208:211], v[54:57]
	v_mfma_f32_16x16x32_bf16 v[50:53], v[200:203], v[208:211], v[50:53]
	v_mfma_f32_16x16x32_bf16 v[38:41], v[190:193], v[216:219], v[38:41]
	v_mfma_f32_16x16x32_bf16 v[34:37], v[200:203], v[216:219], v[34:37]
	v_mfma_f32_16x16x32_bf16 v[22:25], v[190:193], v[224:227], v[22:25]
	v_mfma_f32_16x16x32_bf16 v[18:21], v[200:203], v[224:227], v[18:21]
	v_mfma_f32_16x16x32_bf16 v[6:9], v[190:193], v[232:235], v[6:9]
	v_mfma_f32_16x16x32_bf16 v[2:5], v[200:203], v[232:235], v[2:5]
	s_barrier
	s_add_i32 s56, s56, 2
	s_add_u32 s34, s34, 0x100
	s_addc_u32 s35, s35, 0
	s_add_u32 s54, s54, 0x100
	s_addc_u32 s55, s55, 0
	s_cmp_gt_u32 s56, 61
	s_cbranch_scc0 .LBB0_180
	s_and_b64 vcc, exec, s[12:13]
	s_cbranch_vccz .LBB0_183
	s_barrier

; #define PG8_STAGE(bufoff, gbase, voff) do { _Pragma("unroll") for (int _i = 0; _i < 2; ++_i) \
;         __builtin_amdgcn_global_load_lds((const unsigned*)((const char*)(gbase) + (voff)[_i]), (PG8_LAS unsigned*)(lds + (bufoff) + ldsw + _i * 8192), 16, 0, 0); } while (0)
; #define PG8_LDA(dst, b, h) do { _Pragma("unroll") for (int m = 0; m < 4; ++m) _Pragma("unroll") for (int k = 0; k < 2; ++k) dst[m][k] = *(const PG8_LAS bf16x8*)(lds + PG8_SA(b, h) + aoff + m * 2048 + k * 1024); } while (0)
; #define PG8_LDB(dst, b, h) do { _Pragma("unroll") for (int n = 0; n < 2; ++n) _Pragma("unroll") for (int k = 0; k < 2; ++k) dst[n][k] = *(const PG8_LAS bf16x8*)(lds + PG8_SB(b, h) + boff + n * 2048 + k * 1024); } while (0)
; #define PG8_MMA(ai, bj, At, Bt) do { __builtin_amdgcn_s_setprio(1); _Pragma("unroll") for (int m = 0; m < 4; ++m) _Pragma("unroll") for (int n = 0; n < 2; ++n) _Pragma("unroll") for (int k = 0; k < 2; ++k) \
;         acc[ai][bj][m][n] = __builtin_amdgcn_mfma_f32_16x16x32_bf16(Bt[n][k], At[m][k], acc[ai][bj][m][n], 0, 0, 0); __builtin_amdgcn_s_setprio(0); } while (0)
; #define PG8_WAIT_V(n) asm volatile("s_waitcnt vmcnt(" #n ")" ::: "memory")
; #define PG8_BAR __builtin_amdgcn_s_barrier()
; template <class Epi, class Sched, bool ALIGN_EPI = false, bool SP2 = false>
; __device__ __forceinline__ void gemm_phase(PG8_LAS unsigned char* lds, const Gemm g, const Sched& S, const Epi& E) {
;     ...
;         for (int t = 0; t < nt; t += 2) {
;             const bool last = (t == nt - 2);
;             const char* a1 = cA + (size_t)(t + 1) * kstep;
;             const char* a2 = last ? nA : cA + (size_t)(t + 2) * kstep; const char* b2 = last ? nB : cB + (size_t)(t + 2) * kstep;
;             const char* a3 = a2 + kstep; const char* b3 = b2 + kstep;
;             if (last && has_next) S.a_ready(nxt);
;             if constexpr (SP2) {
;             PG8_LDB(B0, 0, 0); PG8_LDB(B1, 0, 1); PG8_SCHED; PG8_LDA(At, 0, 0); PG8_STAGE(PG8_SA(1, 1), a1 + hstep, voffA);
;             PG8_WAIT_V(8); PG8_WAIT_L(0); PG8_BAR; PG8_MMA(0, 0, At, B0); PG8_MMA(0, 1, At, B1); PG8_BAR; PG8_SCHED;
;             PG8_LDA(At, 0, 1); PG8_STAGE(PG8_SB(0, 0), b2, voffB); PG8_STAGE(PG8_SB(0, 1), b2 + hstep, voffB); PG8_STAGE(PG8_SA(0, 0), a2, voffA);
;             PG8_WAIT_V(8); PG8_WAIT_L(0); PG8_BAR; PG8_MMA(1, 0, At, B0); PG8_MMA(1, 1, At, B1); PG8_BAR; PG8_SCHED;
.LBB0_857:
	s_add_u32 s34, s30, 0xfff80000
	s_addc_u32 s35, s31, -1
	s_mov_b32 m0, s43
	s_nop 0
	global_load_lds_dwordx4 v150, s[34:35]
	s_mov_b32 m0, s44
	s_nop 0
	global_load_lds_dwordx4 v154, s[34:35]
	s_add_u32 s34, s34, 0x80
	s_addc_u32 s35, s35, 0
	ds_read_b128 v[130:133], v180
	ds_read_b128 v[134:137], v180 offset:1024
	ds_read_b128 v[138:141], v180 offset:2048
	ds_read_b128 v[142:145], v180 offset:3072
	ds_read_b128 v[146:149], v181
	ds_read_b128 v[166:169], v181 offset:1024
	ds_read_b128 v[170:173], v181 offset:2048
	ds_read_b128 v[174:177], v181 offset:3072
	s_cmp_eq_u32 s56, 28
	s_cselect_b32 s37, s15, s35
	s_cselect_b32 s36, s50, s34
	s_cselect_b32 s35, s13, s53
	s_cselect_b32 s34, s51, s52
	s_add_i32 m0, s29, 0xc000
	ds_read_b128 v[184:187], v182
	ds_read_b128 v[188:191], v182 offset:1024
	ds_read_b128 v[192:195], v182 offset:2048
	ds_read_b128 v[200:203], v182 offset:3072
	ds_read_b128 v[204:207], v182 offset:4096
	ds_read_b128 v[208:211], v182 offset:5120
	ds_read_b128 v[212:215], v182 offset:6144
	ds_read_b128 v[216:219], v182 offset:7168
	global_load_lds_dwordx4 v158, s[30:31]
	s_add_i32 m0, s29, 0xe000
	s_nop 0
	global_load_lds_dwordx4 v160, s[30:31]
	s_waitcnt vmcnt(8)
	s_waitcnt lgkmcnt(0)
	s_barrier
	v_mfma_f32_16x16x32_bf16 v[126:129], v[130:133], v[184:187], v[126:129]
	v_mfma_f32_16x16x32_bf16 v[122:125], v[138:141], v[184:187], v[122:125]
	v_mfma_f32_16x16x32_bf16 v[110:113], v[130:133], v[192:195], v[110:113]
	v_mfma_f32_16x16x32_bf16 v[106:109], v[138:141], v[192:195], v[106:109]
	v_mfma_f32_16x16x32_bf16 v[94:97], v[130:133], v[204:207], v[94:97]
	v_mfma_f32_16x16x32_bf16 v[90:93], v[138:141], v[204:207], v[90:93]
	v_mfma_f32_16x16x32_bf16 v[78:81], v[130:133], v[212:215], v[78:81]
	v_mfma_f32_16x16x32_bf16 v[74:77], v[138:141], v[212:215], v[74:77]
	v_mfma_f32_16x16x32_bf16 v[126:129], v[134:137], v[188:191], v[126:129]
	v_mfma_f32_16x16x32_bf16 v[122:125], v[142:145], v[188:191], v[122:125]
	v_mfma_f32_16x16x32_bf16 v[110:113], v[134:137], v[200:203], v[110:113]
	v_mfma_f32_16x16x32_bf16 v[106:109], v[142:145], v[200:203], v[106:109]
	v_mfma_f32_16x16x32_bf16 v[94:97], v[134:137], v[208:211], v[94:97]
	v_mfma_f32_16x16x32_bf16 v[90:93], v[142:145], v[208:211], v[90:93]
	v_mfma_f32_16x16x32_bf16 v[78:81], v[134:137], v[216:219], v[78:81]
	v_mfma_f32_16x16x32_bf16 v[74:77], v[142:145], v[216:219], v[74:77]
	v_mfma_f32_16x16x32_bf16 v[118:121], v[146:149], v[184:187], v[118:121]
	v_mfma_f32_16x16x32_bf16 v[114:117], v[170:173], v[184:187], v[114:117]
	v_mfma_f32_16x16x32_bf16 v[102:105], v[146:149], v[192:195], v[102:105]
	v_mfma_f32_16x16x32_bf16 v[98:101], v[170:173], v[192:195], v[98:101]
	v_mfma_f32_16x16x32_bf16 v[86:89], v[146:149], v[204:207], v[86:89]
	v_mfma_f32_16x16x32_bf16 v[82:85], v[170:173], v[204:207], v[82:85]
	v_mfma_f32_16x16x32_bf16 v[70:73], v[146:149], v[212:215], v[70:73]
	v_mfma_f32_16x16x32_bf16 v[66:69], v[170:173], v[212:215], v[66:69]
	v_mfma_f32_16x16x32_bf16 v[118:121], v[166:169], v[188:191], v[118:121]
	v_mfma_f32_16x16x32_bf16 v[114:117], v[174:177], v[188:191], v[114:117]
	v_mfma_f32_16x16x32_bf16 v[102:105], v[166:169], v[200:203], v[102:105]
	v_mfma_f32_16x16x32_bf16 v[98:101], v[174:177], v[200:203], v[98:101]
	v_mfma_f32_16x16x32_bf16 v[86:89], v[166:169], v[208:211], v[86:89]
	v_mfma_f32_16x16x32_bf16 v[82:85], v[174:177], v[208:211], v[82:85]
	v_mfma_f32_16x16x32_bf16 v[70:73], v[166:169], v[216:219], v[70:73]
	v_mfma_f32_16x16x32_bf16 v[66:69], v[174:177], v[216:219], v[66:69]
	s_barrier
	s_add_i32 s57, s46, s38
	v_lshl_add_u64 v[196:197], s[34:35], 0, v[152:153]
	s_mov_b32 m0, s57
	ds_read_b128 v[184:187], v182 offset:16384
	ds_read_b128 v[188:191], v182 offset:17408
	ds_read_b128 v[192:195], v182 offset:18432
	ds_read_b128 v[200:203], v182 offset:19456
	ds_read_b128 v[204:207], v182 offset:20480
	ds_read_b128 v[208:211], v182 offset:21504
	ds_read_b128 v[212:215], v182 offset:22528
	ds_read_b128 v[216:219], v182 offset:23552
	global_load_lds_dwordx4 v152, s[34:35]
	s_add_i32 m0, s57, 0x2000
	s_add_u32 s58, s34, 0x80000
	v_lshl_add_u64 v[220:221], s[34:35], 0, v[156:157]
	s_addc_u32 s59, s35, 0
	s_add_i32 s57, s47, s38
	global_load_lds_dwordx4 v156, s[34:35]
	s_mov_b32 m0, s57
	s_nop 0
	global_load_lds_dwordx4 v152, s[58:59]
	s_add_i32 m0, s57, 0x2000
	s_nop 0
	global_load_lds_dwordx4 v156, s[58:59]
	s_waitcnt vmcnt(6)
	s_waitcnt lgkmcnt(0)
	s_barrier
	v_mfma_f32_16x16x32_bf16 v[62:65], v[130:133], v[184:187], v[62:65]
	v_mfma_f32_16x16x32_bf16 v[58:61], v[138:141], v[184:187], v[58:61]
	v_mfma_f32_16x16x32_bf16 v[46:49], v[130:133], v[192:195], v[46:49]
	v_mfma_f32_16x16x32_bf16 v[42:45], v[138:141], v[192:195], v[42:45]
	v_mfma_f32_16x16x32_bf16 v[30:33], v[130:133], v[204:207], v[30:33]
	v_mfma_f32_16x16x32_bf16 v[26:29], v[138:141], v[204:207], v[26:29]
	v_mfma_f32_16x16x32_bf16 v[14:17], v[130:133], v[212:215], v[14:17]
	v_mfma_f32_16x16x32_bf16 v[10:13], v[138:141], v[212:215], v[10:13]
	v_mfma_f32_16x16x32_bf16 v[62:65], v[134:137], v[188:191], v[62:65]
	v_mfma_f32_16x16x32_bf16 v[58:61], v[142:145], v[188:191], v[58:61]
	v_mfma_f32_16x16x32_bf16 v[46:49], v[134:137], v[200:203], v[46:49]
	v_mfma_f32_16x16x32_bf16 v[42:45], v[142:145], v[200:203], v[42:45]
	v_mfma_f32_16x16x32_bf16 v[30:33], v[134:137], v[208:211], v[30:33]
	v_mfma_f32_16x16x32_bf16 v[26:29], v[142:145], v[208:211], v[26:29]
	v_mfma_f32_16x16x32_bf16 v[14:17], v[134:137], v[216:219], v[14:17]
	v_mfma_f32_16x16x32_bf16 v[10:13], v[142:145], v[216:219], v[10:13]
	v_mfma_f32_16x16x32_bf16 v[54:57], v[146:149], v[184:187], v[54:57]
	v_mfma_f32_16x16x32_bf16 v[50:53], v[170:173], v[184:187], v[50:53]
	v_mfma_f32_16x16x32_bf16 v[38:41], v[146:149], v[192:195], v[38:41]
	v_mfma_f32_16x16x32_bf16 v[34:37], v[170:173], v[192:195], v[34:37]
	v_mfma_f32_16x16x32_bf16 v[22:25], v[146:149], v[204:207], v[22:25]
	v_mfma_f32_16x16x32_bf16 v[18:21], v[170:173], v[204:207], v[18:21]
	v_mfma_f32_16x16x32_bf16 v[6:9], v[146:149], v[212:215], v[6:9]
	v_mfma_f32_16x16x32_bf16 v[2:5], v[170:173], v[212:215], v[2:5]
	v_mfma_f32_16x16x32_bf16 v[54:57], v[166:169], v[188:191], v[54:57]
	v_mfma_f32_16x16x32_bf16 v[50:53], v[174:177], v[188:191], v[50:53]
	v_mfma_f32_16x16x32_bf16 v[38:41], v[166:169], v[200:203], v[38:41]
	v_mfma_f32_16x16x32_bf16 v[34:37], v[174:177], v[200:203], v[34:37]
	v_mfma_f32_16x16x32_bf16 v[22:25], v[166:169], v[208:211], v[22:25]
	v_mfma_f32_16x16x32_bf16 v[18:21], v[174:177], v[208:211], v[18:21]
	v_mfma_f32_16x16x32_bf16 v[6:9], v[166:169], v[216:219], v[6:9]
	v_mfma_f32_16x16x32_bf16 v[2:5], v[174:177], v[216:219], v[2:5]
	s_barrier
; #define PG8_STAGE(bufoff, gbase, voff) do { _Pragma("unroll") for (int _i = 0; _i < 2; ++_i) \
;         __builtin_amdgcn_global_load_lds((const unsigned*)((const char*)(gbase) + (voff)[_i]), (PG8_LAS unsigned*)(lds + (bufoff) + ldsw + _i * 8192), 16, 0, 0); } while (0)
; #define PG8_LDA(dst, b, h) do { _Pragma("unroll") for (int m = 0; m < 4; ++m) _Pragma("unroll") for (int k = 0; k < 2; ++k) dst[m][k] = *(const PG8_LAS bf16x8*)(lds + PG8_SA(b, h) + aoff + m * 2048 + k * 1024); } while (0)
; #define PG8_LDB(dst, b, h) do { _Pragma("unroll") for (int n = 0; n < 2; ++n) _Pragma("unroll") for (int k = 0; k < 2; ++k) dst[n][k] = *(const PG8_LAS bf16x8*)(lds + PG8_SB(b, h) + boff + n * 2048 + k * 1024); } while (0)
; #define PG8_MMA(ai, bj, At, Bt) do { __builtin_amdgcn_s_setprio(1); _Pragma("unroll") for (int m = 0; m < 4; ++m) _Pragma("unroll") for (int n = 0; n < 2; ++n) _Pragma("unroll") for (int k = 0; k < 2; ++k) \
;         acc[ai][bj][m][n] = __builtin_amdgcn_mfma_f32_16x16x32_bf16(Bt[n][k], At[m][k], acc[ai][bj][m][n], 0, 0, 0); __builtin_amdgcn_s_setprio(0); } while (0)
; #define PG8_WAIT_V(n) asm volatile("s_waitcnt vmcnt(" #n ")" ::: "memory")
; #define PG8_WAIT_L(n) asm volatile("s_waitcnt lgkmcnt(" #n ")" ::: "memory")
; #define PG8_BAR __builtin_amdgcn_s_barrier()
; #define PG8_SCHED __builtin_amdgcn_sched_barrier(0)
; template <class Epi, class Sched, bool ALIGN_EPI = false, bool SP2 = false>
; __device__ __forceinline__ void gemm_phase(PG8_LAS unsigned char* lds, const Gemm g, const Sched& S, const Epi& E) {
;     ...
;             PG8_LDB(B0, 1, 0); PG8_LDB(B1, 1, 1); PG8_SCHED; PG8_LDA(At, 1, 0); PG8_STAGE(PG8_SA(0, 1), a2 + hstep, voffA);
;             PG8_WAIT_V(8); PG8_WAIT_L(0); PG8_BAR; PG8_MMA(0, 0, At, B0); PG8_MMA(0, 1, At, B1); PG8_BAR; PG8_SCHED;
;             PG8_LDA(At, 1, 1); PG8_STAGE(PG8_SB(1, 0), b3, voffB); PG8_STAGE(PG8_SB(1, 1), b3 + hstep, voffB); PG8_STAGE(PG8_SA(1, 0), a3, voffA);
;             PG8_WAIT_V(8); PG8_WAIT_L(0); PG8_BAR; PG8_MMA(1, 0, At, B0); PG8_MMA(1, 1, At, B1); PG8_BAR; PG8_SCHED;
	s_mov_b32 m0, s29
	s_nop 0
	global_load_lds_dwordx4 v150, s[36:37]
	s_mov_b32 m0, s39
	s_nop 0
	global_load_lds_dwordx4 v154, s[36:37]
	s_add_i32 s57, 0, 0x18000
	s_add_i32 s58, 0, 0x1c000
	v_add_u32_e32 v142, s57, v178
	v_add_u32_e32 v174, s58, v178
	ds_read_b128 v[130:133], v142
	ds_read_b128 v[134:137], v142 offset:1024
	ds_read_b128 v[138:141], v142 offset:2048
	ds_read_b128 v[142:145], v142 offset:3072
	ds_read_b128 v[146:149], v174
	ds_read_b128 v[166:169], v174 offset:1024
	ds_read_b128 v[170:173], v174 offset:2048
	ds_read_b128 v[174:177], v174 offset:3072
	s_add_u32 s36, s36, 0x80000
	s_addc_u32 s37, s37, 0
	s_mov_b32 m0, s40
	ds_read_b128 v[184:187], v182 offset:32768
	ds_read_b128 v[188:191], v182 offset:33792
	ds_read_b128 v[192:195], v182 offset:34816
	ds_read_b128 v[200:203], v182 offset:35840
	ds_read_b128 v[204:207], v182 offset:36864
	ds_read_b128 v[208:211], v182 offset:37888
	ds_read_b128 v[212:215], v182 offset:38912
	ds_read_b128 v[216:219], v182 offset:39936
	global_load_lds_dwordx4 v150, s[36:37]
	s_mov_b32 m0, s41
	s_nop 0
	global_load_lds_dwordx4 v154, s[36:37]
	s_waitcnt vmcnt(8)
	s_waitcnt lgkmcnt(0)
	s_barrier
	v_mfma_f32_16x16x32_bf16 v[126:129], v[130:133], v[184:187], v[126:129]
	v_mfma_f32_16x16x32_bf16 v[122:125], v[138:141], v[184:187], v[122:125]
	v_mfma_f32_16x16x32_bf16 v[110:113], v[130:133], v[192:195], v[110:113]
	v_mfma_f32_16x16x32_bf16 v[106:109], v[138:141], v[192:195], v[106:109]
	v_mfma_f32_16x16x32_bf16 v[94:97], v[130:133], v[204:207], v[94:97]
	v_mfma_f32_16x16x32_bf16 v[90:93], v[138:141], v[204:207], v[90:93]
	v_mfma_f32_16x16x32_bf16 v[78:81], v[130:133], v[212:215], v[78:81]
	v_mfma_f32_16x16x32_bf16 v[74:77], v[138:141], v[212:215], v[74:77]
	v_mfma_f32_16x16x32_bf16 v[126:129], v[134:137], v[188:191], v[126:129]
	v_mfma_f32_16x16x32_bf16 v[122:125], v[142:145], v[188:191], v[122:125]
	v_mfma_f32_16x16x32_bf16 v[110:113], v[134:137], v[200:203], v[110:113]
	v_mfma_f32_16x16x32_bf16 v[106:109], v[142:145], v[200:203], v[106:109]
	v_mfma_f32_16x16x32_bf16 v[94:97], v[134:137], v[208:211], v[94:97]
	v_mfma_f32_16x16x32_bf16 v[90:93], v[142:145], v[208:211], v[90:93]
	v_mfma_f32_16x16x32_bf16 v[78:81], v[134:137], v[216:219], v[78:81]
	v_mfma_f32_16x16x32_bf16 v[74:77], v[142:145], v[216:219], v[74:77]
	v_mfma_f32_16x16x32_bf16 v[118:121], v[146:149], v[184:187], v[118:121]
	v_mfma_f32_16x16x32_bf16 v[114:117], v[170:173], v[184:187], v[114:117]
	v_mfma_f32_16x16x32_bf16 v[102:105], v[146:149], v[192:195], v[102:105]
	v_mfma_f32_16x16x32_bf16 v[98:101], v[170:173], v[192:195], v[98:101]
	v_mfma_f32_16x16x32_bf16 v[86:89], v[146:149], v[204:207], v[86:89]
	v_mfma_f32_16x16x32_bf16 v[82:85], v[170:173], v[204:207], v[82:85]
	v_mfma_f32_16x16x32_bf16 v[70:73], v[146:149], v[212:215], v[70:73]
	v_mfma_f32_16x16x32_bf16 v[66:69], v[170:173], v[212:215], v[66:69]
	v_mfma_f32_16x16x32_bf16 v[118:121], v[166:169], v[188:191], v[118:121]
	v_mfma_f32_16x16x32_bf16 v[114:117], v[174:177], v[188:191], v[114:117]
	v_mfma_f32_16x16x32_bf16 v[102:105], v[166:169], v[200:203], v[102:105]
	v_mfma_f32_16x16x32_bf16 v[98:101], v[174:177], v[200:203], v[98:101]
	v_mfma_f32_16x16x32_bf16 v[86:89], v[166:169], v[208:211], v[86:89]
	v_mfma_f32_16x16x32_bf16 v[82:85], v[174:177], v[208:211], v[82:85]
	v_mfma_f32_16x16x32_bf16 v[70:73], v[166:169], v[216:219], v[70:73]
	v_mfma_f32_16x16x32_bf16 v[66:69], v[174:177], v[216:219], v[66:69]
	s_barrier
	s_add_i32 s36, s57, s38
	v_lshl_add_u64 v[196:197], v[196:197], 0, s[8:9]
	s_mov_b32 m0, s36
	ds_read_b128 v[184:187], v182 offset:49152
	ds_read_b128 v[188:191], v182 offset:50176
	ds_read_b128 v[192:195], v182 offset:51200
	ds_read_b128 v[200:203], v182 offset:52224
	ds_read_b128 v[204:207], v182 offset:53248
	ds_read_b128 v[208:211], v182 offset:54272
	ds_read_b128 v[212:215], v182 offset:55296
	ds_read_b128 v[216:219], v182 offset:56320
	global_load_lds_dwordx4 v[196:197], off
	s_add_i32 m0, s36, 0x2000
	s_add_u32 s34, s34, 0x80080
	v_lshl_add_u64 v[196:197], v[220:221], 0, s[8:9]
	s_addc_u32 s35, s35, 0
	s_add_i32 s36, s58, s38
	global_load_lds_dwordx4 v[196:197], off
	s_mov_b32 m0, s36
	s_nop 0
	global_load_lds_dwordx4 v152, s[34:35]
	s_add_i32 m0, s36, 0x2000
	s_nop 0
	global_load_lds_dwordx4 v156, s[34:35]
	s_waitcnt vmcnt(6)
	s_waitcnt lgkmcnt(0)
	s_barrier
	v_mfma_f32_16x16x32_bf16 v[62:65], v[130:133], v[184:187], v[62:65]
	v_mfma_f32_16x16x32_bf16 v[58:61], v[138:141], v[184:187], v[58:61]
	v_mfma_f32_16x16x32_bf16 v[46:49], v[130:133], v[192:195], v[46:49]
	v_mfma_f32_16x16x32_bf16 v[42:45], v[138:141], v[192:195], v[42:45]
	v_mfma_f32_16x16x32_bf16 v[30:33], v[130:133], v[204:207], v[30:33]
	v_mfma_f32_16x16x32_bf16 v[26:29], v[138:141], v[204:207], v[26:29]
	v_mfma_f32_16x16x32_bf16 v[14:17], v[130:133], v[212:215], v[14:17]
	v_mfma_f32_16x16x32_bf16 v[10:13], v[138:141], v[212:215], v[10:13]
	v_mfma_f32_16x16x32_bf16 v[62:65], v[134:137], v[188:191], v[62:65]
	v_mfma_f32_16x16x32_bf16 v[58:61], v[142:145], v[188:191], v[58:61]
	v_mfma_f32_16x16x32_bf16 v[46:49], v[134:137], v[200:203], v[46:49]
	v_mfma_f32_16x16x32_bf16 v[42:45], v[142:145], v[200:203], v[42:45]
	v_mfma_f32_16x16x32_bf16 v[30:33], v[134:137], v[208:211], v[30:33]
	v_mfma_f32_16x16x32_bf16 v[26:29], v[142:145], v[208:211], v[26:29]
	v_mfma_f32_16x16x32_bf16 v[14:17], v[134:137], v[216:219], v[14:17]
	v_mfma_f32_16x16x32_bf16 v[10:13], v[142:145], v[216:219], v[10:13]
	v_mfma_f32_16x16x32_bf16 v[54:57], v[146:149], v[184:187], v[54:57]
	v_mfma_f32_16x16x32_bf16 v[50:53], v[170:173], v[184:187], v[50:53]
	v_mfma_f32_16x16x32_bf16 v[38:41], v[146:149], v[192:195], v[38:41]
	v_mfma_f32_16x16x32_bf16 v[34:37], v[170:173], v[192:195], v[34:37]
	v_mfma_f32_16x16x32_bf16 v[22:25], v[146:149], v[204:207], v[22:25]
	v_mfma_f32_16x16x32_bf16 v[18:21], v[170:173], v[204:207], v[18:21]
	v_mfma_f32_16x16x32_bf16 v[6:9], v[146:149], v[212:215], v[6:9]
	v_mfma_f32_16x16x32_bf16 v[2:5], v[170:173], v[212:215], v[2:5]
	v_mfma_f32_16x16x32_bf16 v[54:57], v[166:169], v[188:191], v[54:57]
	v_mfma_f32_16x16x32_bf16 v[50:53], v[174:177], v[188:191], v[50:53]
	v_mfma_f32_16x16x32_bf16 v[38:41], v[166:169], v[200:203], v[38:41]
	v_mfma_f32_16x16x32_bf16 v[34:37], v[174:177], v[200:203], v[34:37]
	v_mfma_f32_16x16x32_bf16 v[22:25], v[166:169], v[208:211], v[22:25]
	v_mfma_f32_16x16x32_bf16 v[18:21], v[174:177], v[208:211], v[18:21]
	v_mfma_f32_16x16x32_bf16 v[6:9], v[166:169], v[216:219], v[6:9]
	v_mfma_f32_16x16x32_bf16 v[2:5], v[174:177], v[216:219], v[2:5]
	s_barrier
	s_add_i32 s56, s56, 2
	s_add_u32 s30, s30, 0x100
	s_addc_u32 s31, s31, 0
	s_add_u32 s52, s52, 0x100
	s_addc_u32 s53, s53, 0
	s_cmp_gt_u32 s56, 29
	s_cbranch_scc0 .LBB0_857
	s_and_b64 vcc, exec, s[10:11]
	s_cbranch_vccz .LBB0_860
	s_barrier

; #define PG8_STAGE(bufoff, gbase, voff) do { _Pragma("unroll") for (int _i = 0; _i < 2; ++_i) \
;         __builtin_amdgcn_global_load_lds((const unsigned*)((const char*)(gbase) + (voff)[_i]), (PG8_LAS unsigned*)(lds + (bufoff) + ldsw + _i * 8192), 16, 0, 0); } while (0)
; #define PG8_LDA(dst, b, h) do { _Pragma("unroll") for (int m = 0; m < 4; ++m) _Pragma("unroll") for (int k = 0; k < 2; ++k) dst[m][k] = *(const PG8_LAS bf16x8*)(lds + PG8_SA(b, h) + aoff + m * 2048 + k * 1024); } while (0)
; #define PG8_LDB(dst, b, h) do { _Pragma("unroll") for (int n = 0; n < 2; ++n) _Pragma("unroll") for (int k = 0; k < 2; ++k) dst[n][k] = *(const PG8_LAS bf16x8*)(lds + PG8_SB(b, h) + boff + n * 2048 + k * 1024); } while (0)
; #define PG8_MMA(ai, bj, At, Bt) do { __builtin_amdgcn_s_setprio(1); _Pragma("unroll") for (int m = 0; m < 4; ++m) _Pragma("unroll") for (int n = 0; n < 2; ++n) _Pragma("unroll") for (int k = 0; k < 2; ++k) \
;         acc[ai][bj][m][n] = __builtin_amdgcn_mfma_f32_16x16x32_bf16(Bt[n][k], At[m][k], acc[ai][bj][m][n], 0, 0, 0); __builtin_amdgcn_s_setprio(0); } while (0)
; #define PG8_WAIT_V(n) asm volatile("s_waitcnt vmcnt(" #n ")" ::: "memory")
; #define PG8_BAR __builtin_amdgcn_s_barrier()
; template <class Epi, class Sched, bool ALIGN_EPI = false, bool SP2 = false>
; __device__ __forceinline__ void gemm_phase(PG8_LAS unsigned char* lds, const Gemm g, const Sched& S, const Epi& E) {
;     ...
;         for (int t = 0; t < nt; t += 2) {
;             const bool last = (t == nt - 2);
;             const char* a1 = cA + (size_t)(t + 1) * kstep;
;             const char* a2 = last ? nA : cA + (size_t)(t + 2) * kstep; const char* b2 = last ? nB : cB + (size_t)(t + 2) * kstep;
;             const char* a3 = a2 + kstep; const char* b3 = b2 + kstep;
;             if (last && has_next) S.a_ready(nxt);
;             if constexpr (SP2) {
;             PG8_LDB(B0, 0, 0); PG8_LDB(B1, 0, 1); PG8_SCHED; PG8_LDA(At, 0, 0); PG8_STAGE(PG8_SA(1, 1), a1 + hstep, voffA);
;             PG8_WAIT_V(8); PG8_WAIT_L(0); PG8_BAR; PG8_MMA(0, 0, At, B0); PG8_MMA(0, 1, At, B1); PG8_BAR; PG8_SCHED;
;             PG8_LDA(At, 0, 1); PG8_STAGE(PG8_SB(0, 0), b2, voffB); PG8_STAGE(PG8_SB(0, 1), b2 + hstep, voffB); PG8_STAGE(PG8_SA(0, 0), a2, voffA);
;             PG8_WAIT_V(8); PG8_WAIT_L(0); PG8_BAR; PG8_MMA(1, 0, At, B0); PG8_MMA(1, 1, At, B1); PG8_BAR; PG8_SCHED;
.LBB0_884:
	s_add_u32 s34, s30, 0xfff80000
	s_addc_u32 s35, s31, -1
	s_mov_b32 m0, s43
	s_nop 0
	global_load_lds_dwordx4 v178, s[34:35]
	s_mov_b32 m0, s44
	s_nop 0
	global_load_lds_dwordx4 v182, s[34:35]
	s_add_u32 s34, s34, 0x80
	s_addc_u32 s35, s35, 0
	ds_read_b128 v[130:133], v211
	ds_read_b128 v[134:137], v211 offset:1024
	ds_read_b128 v[138:141], v211 offset:2048
	ds_read_b128 v[142:145], v211 offset:3072
	ds_read_b128 v[146:149], v212
	ds_read_b128 v[150:153], v212 offset:1024
	ds_read_b128 v[154:157], v212 offset:2048
	ds_read_b128 v[158:161], v212 offset:3072
	s_cmp_eq_u32 s56, 28
	s_cselect_b32 s37, s15, s35
	s_cselect_b32 s36, s50, s34
	s_cselect_b32 s35, s13, s53
	s_cselect_b32 s34, s51, s52
	s_add_i32 m0, s29, 0xc000
	ds_read_b128 v[162:165], v213
	ds_read_b128 v[166:169], v213 offset:1024
	ds_read_b128 v[170:173], v213 offset:2048
	ds_read_b128 v[174:177], v213 offset:3072
	ds_read_b128 v[194:197], v213 offset:4096
	ds_read_b128 v[200:203], v213 offset:5120
	ds_read_b128 v[204:207], v213 offset:6144
	ds_read_b128 v[214:217], v213 offset:7168
	global_load_lds_dwordx4 v186, s[30:31]
	s_add_i32 m0, s29, 0xe000
	s_nop 0
	global_load_lds_dwordx4 v188, s[30:31]
	s_waitcnt vmcnt(8)
	s_waitcnt lgkmcnt(0)
	s_barrier
	v_mfma_f32_16x16x32_bf16 v[126:129], v[130:133], v[162:165], v[126:129]
	v_mfma_f32_16x16x32_bf16 v[122:125], v[138:141], v[162:165], v[122:125]
	v_mfma_f32_16x16x32_bf16 v[110:113], v[130:133], v[170:173], v[110:113]
	v_mfma_f32_16x16x32_bf16 v[106:109], v[138:141], v[170:173], v[106:109]
	v_mfma_f32_16x16x32_bf16 v[94:97], v[130:133], v[194:197], v[94:97]
	v_mfma_f32_16x16x32_bf16 v[90:93], v[138:141], v[194:197], v[90:93]
	v_mfma_f32_16x16x32_bf16 v[78:81], v[130:133], v[204:207], v[78:81]
	v_mfma_f32_16x16x32_bf16 v[74:77], v[138:141], v[204:207], v[74:77]
	v_mfma_f32_16x16x32_bf16 v[126:129], v[134:137], v[166:169], v[126:129]
	v_mfma_f32_16x16x32_bf16 v[122:125], v[142:145], v[166:169], v[122:125]
	v_mfma_f32_16x16x32_bf16 v[110:113], v[134:137], v[174:177], v[110:113]
	v_mfma_f32_16x16x32_bf16 v[106:109], v[142:145], v[174:177], v[106:109]
	v_mfma_f32_16x16x32_bf16 v[94:97], v[134:137], v[200:203], v[94:97]
	v_mfma_f32_16x16x32_bf16 v[90:93], v[142:145], v[200:203], v[90:93]
	v_mfma_f32_16x16x32_bf16 v[78:81], v[134:137], v[214:217], v[78:81]
	v_mfma_f32_16x16x32_bf16 v[74:77], v[142:145], v[214:217], v[74:77]
	v_mfma_f32_16x16x32_bf16 v[118:121], v[146:149], v[162:165], v[118:121]
	v_mfma_f32_16x16x32_bf16 v[114:117], v[154:157], v[162:165], v[114:117]
	v_mfma_f32_16x16x32_bf16 v[102:105], v[146:149], v[170:173], v[102:105]
	v_mfma_f32_16x16x32_bf16 v[98:101], v[154:157], v[170:173], v[98:101]
	v_mfma_f32_16x16x32_bf16 v[86:89], v[146:149], v[194:197], v[86:89]
	v_mfma_f32_16x16x32_bf16 v[82:85], v[154:157], v[194:197], v[82:85]
	v_mfma_f32_16x16x32_bf16 v[70:73], v[146:149], v[204:207], v[70:73]
	v_mfma_f32_16x16x32_bf16 v[66:69], v[154:157], v[204:207], v[66:69]
	v_mfma_f32_16x16x32_bf16 v[118:121], v[150:153], v[166:169], v[118:121]
	v_mfma_f32_16x16x32_bf16 v[114:117], v[158:161], v[166:169], v[114:117]
	v_mfma_f32_16x16x32_bf16 v[102:105], v[150:153], v[174:177], v[102:105]
	v_mfma_f32_16x16x32_bf16 v[98:101], v[158:161], v[174:177], v[98:101]
	v_mfma_f32_16x16x32_bf16 v[86:89], v[150:153], v[200:203], v[86:89]
	v_mfma_f32_16x16x32_bf16 v[82:85], v[158:161], v[200:203], v[82:85]
	v_mfma_f32_16x16x32_bf16 v[70:73], v[150:153], v[214:217], v[70:73]
	v_mfma_f32_16x16x32_bf16 v[66:69], v[158:161], v[214:217], v[66:69]
	s_barrier
	s_add_i32 s57, s46, s38
	v_lshl_add_u64 v[208:209], s[34:35], 0, v[180:181]
	s_mov_b32 m0, s57
	ds_read_b128 v[162:165], v213 offset:16384
	ds_read_b128 v[166:169], v213 offset:17408
	ds_read_b128 v[170:173], v213 offset:18432
	ds_read_b128 v[174:177], v213 offset:19456
	ds_read_b128 v[194:197], v213 offset:20480
	ds_read_b128 v[200:203], v213 offset:21504
	ds_read_b128 v[204:207], v213 offset:22528
	ds_read_b128 v[214:217], v213 offset:23552
	global_load_lds_dwordx4 v180, s[34:35]
	s_add_i32 m0, s57, 0x2000
	s_add_u32 s58, s34, 0x80000
	v_lshl_add_u64 v[218:219], s[34:35], 0, v[184:185]
	s_addc_u32 s59, s35, 0
	s_add_i32 s57, s47, s38
	global_load_lds_dwordx4 v184, s[34:35]
	s_mov_b32 m0, s57
	s_nop 0
	global_load_lds_dwordx4 v180, s[58:59]
	s_add_i32 m0, s57, 0x2000
	s_nop 0
	global_load_lds_dwordx4 v184, s[58:59]
	s_waitcnt vmcnt(6)
	s_waitcnt lgkmcnt(0)
	s_barrier
	v_mfma_f32_16x16x32_bf16 v[62:65], v[130:133], v[162:165], v[62:65]
	v_mfma_f32_16x16x32_bf16 v[58:61], v[138:141], v[162:165], v[58:61]
	v_mfma_f32_16x16x32_bf16 v[46:49], v[130:133], v[170:173], v[46:49]
	v_mfma_f32_16x16x32_bf16 v[42:45], v[138:141], v[170:173], v[42:45]
	v_mfma_f32_16x16x32_bf16 v[30:33], v[130:133], v[194:197], v[30:33]
	v_mfma_f32_16x16x32_bf16 v[26:29], v[138:141], v[194:197], v[26:29]
	v_mfma_f32_16x16x32_bf16 v[14:17], v[130:133], v[204:207], v[14:17]
	v_mfma_f32_16x16x32_bf16 v[10:13], v[138:141], v[204:207], v[10:13]
	v_mfma_f32_16x16x32_bf16 v[62:65], v[134:137], v[166:169], v[62:65]
	v_mfma_f32_16x16x32_bf16 v[58:61], v[142:145], v[166:169], v[58:61]
	v_mfma_f32_16x16x32_bf16 v[46:49], v[134:137], v[174:177], v[46:49]
	v_mfma_f32_16x16x32_bf16 v[42:45], v[142:145], v[174:177], v[42:45]
	v_mfma_f32_16x16x32_bf16 v[30:33], v[134:137], v[200:203], v[30:33]
	v_mfma_f32_16x16x32_bf16 v[26:29], v[142:145], v[200:203], v[26:29]
	v_mfma_f32_16x16x32_bf16 v[14:17], v[134:137], v[214:217], v[14:17]
	v_mfma_f32_16x16x32_bf16 v[10:13], v[142:145], v[214:217], v[10:13]
	v_mfma_f32_16x16x32_bf16 v[54:57], v[146:149], v[162:165], v[54:57]
	v_mfma_f32_16x16x32_bf16 v[50:53], v[154:157], v[162:165], v[50:53]
	v_mfma_f32_16x16x32_bf16 v[38:41], v[146:149], v[170:173], v[38:41]
	v_mfma_f32_16x16x32_bf16 v[34:37], v[154:157], v[170:173], v[34:37]
	v_mfma_f32_16x16x32_bf16 v[22:25], v[146:149], v[194:197], v[22:25]
	v_mfma_f32_16x16x32_bf16 v[18:21], v[154:157], v[194:197], v[18:21]
	v_mfma_f32_16x16x32_bf16 v[6:9], v[146:149], v[204:207], v[6:9]
	v_mfma_f32_16x16x32_bf16 v[2:5], v[154:157], v[204:207], v[2:5]
	v_mfma_f32_16x16x32_bf16 v[54:57], v[150:153], v[166:169], v[54:57]
	v_mfma_f32_16x16x32_bf16 v[50:53], v[158:161], v[166:169], v[50:53]
	v_mfma_f32_16x16x32_bf16 v[38:41], v[150:153], v[174:177], v[38:41]
	v_mfma_f32_16x16x32_bf16 v[34:37], v[158:161], v[174:177], v[34:37]
	v_mfma_f32_16x16x32_bf16 v[22:25], v[150:153], v[200:203], v[22:25]
	v_mfma_f32_16x16x32_bf16 v[18:21], v[158:161], v[200:203], v[18:21]
	v_mfma_f32_16x16x32_bf16 v[6:9], v[150:153], v[214:217], v[6:9]
	v_mfma_f32_16x16x32_bf16 v[2:5], v[158:161], v[214:217], v[2:5]
	s_barrier
; #define PG8_STAGE(bufoff, gbase, voff) do { _Pragma("unroll") for (int _i = 0; _i < 2; ++_i) \
;         __builtin_amdgcn_global_load_lds((const unsigned*)((const char*)(gbase) + (voff)[_i]), (PG8_LAS unsigned*)(lds + (bufoff) + ldsw + _i * 8192), 16, 0, 0); } while (0)
; #define PG8_LDA(dst, b, h) do { _Pragma("unroll") for (int m = 0; m < 4; ++m) _Pragma("unroll") for (int k = 0; k < 2; ++k) dst[m][k] = *(const PG8_LAS bf16x8*)(lds + PG8_SA(b, h) + aoff + m * 2048 + k * 1024); } while (0)
; #define PG8_LDB(dst, b, h) do { _Pragma("unroll") for (int n = 0; n < 2; ++n) _Pragma("unroll") for (int k = 0; k < 2; ++k) dst[n][k] = *(const PG8_LAS bf16x8*)(lds + PG8_SB(b, h) + boff + n * 2048 + k * 1024); } while (0)
; #define PG8_MMA(ai, bj, At, Bt) do { __builtin_amdgcn_s_setprio(1); _Pragma("unroll") for (int m = 0; m < 4; ++m) _Pragma("unroll") for (int n = 0; n < 2; ++n) _Pragma("unroll") for (int k = 0; k < 2; ++k) \
;         acc[ai][bj][m][n] = __builtin_amdgcn_mfma_f32_16x16x32_bf16(Bt[n][k], At[m][k], acc[ai][bj][m][n], 0, 0, 0); __builtin_amdgcn_s_setprio(0); } while (0)
; #define PG8_WAIT_V(n) asm volatile("s_waitcnt vmcnt(" #n ")" ::: "memory")
; #define PG8_WAIT_L(n) asm volatile("s_waitcnt lgkmcnt(" #n ")" ::: "memory")
; #define PG8_BAR __builtin_amdgcn_s_barrier()
; #define PG8_SCHED __builtin_amdgcn_sched_barrier(0)
; template <class Epi, class Sched, bool ALIGN_EPI = false, bool SP2 = false>
; __device__ __forceinline__ void gemm_phase(PG8_LAS unsigned char* lds, const Gemm g, const Sched& S, const Epi& E) {
;     ...
;             PG8_LDB(B0, 1, 0); PG8_LDB(B1, 1, 1); PG8_SCHED; PG8_LDA(At, 1, 0); PG8_STAGE(PG8_SA(0, 1), a2 + hstep, voffA);
;             PG8_WAIT_V(8); PG8_WAIT_L(0); PG8_BAR; PG8_MMA(0, 0, At, B0); PG8_MMA(0, 1, At, B1); PG8_BAR; PG8_SCHED;
;             PG8_LDA(At, 1, 1); PG8_STAGE(PG8_SB(1, 0), b3, voffB); PG8_STAGE(PG8_SB(1, 1), b3 + hstep, voffB); PG8_STAGE(PG8_SA(1, 0), a3, voffA);
;             PG8_WAIT_V(8); PG8_WAIT_L(0); PG8_BAR; PG8_MMA(1, 0, At, B0); PG8_MMA(1, 1, At, B1); PG8_BAR; PG8_SCHED;
	s_mov_b32 m0, s29
	s_nop 0
	global_load_lds_dwordx4 v178, s[36:37]
	s_mov_b32 m0, s39
	s_nop 0
	global_load_lds_dwordx4 v182, s[36:37]
	s_add_i32 s57, 0, 0x18000
	s_add_i32 s58, 0, 0x1c000
	v_add_u32_e32 v142, s57, v199
	v_add_u32_e32 v158, s58, v199
	ds_read_b128 v[130:133], v142
	ds_read_b128 v[134:137], v142 offset:1024
	ds_read_b128 v[138:141], v142 offset:2048
	ds_read_b128 v[142:145], v142 offset:3072
	ds_read_b128 v[146:149], v158
	ds_read_b128 v[150:153], v158 offset:1024
	ds_read_b128 v[154:157], v158 offset:2048
	ds_read_b128 v[158:161], v158 offset:3072
	s_add_u32 s36, s36, 0x80000
	s_addc_u32 s37, s37, 0
	s_mov_b32 m0, s40
	ds_read_b128 v[162:165], v213 offset:32768
	ds_read_b128 v[166:169], v213 offset:33792
	ds_read_b128 v[170:173], v213 offset:34816
	ds_read_b128 v[174:177], v213 offset:35840
	ds_read_b128 v[194:197], v213 offset:36864
	ds_read_b128 v[200:203], v213 offset:37888
	ds_read_b128 v[204:207], v213 offset:38912
	ds_read_b128 v[214:217], v213 offset:39936
	global_load_lds_dwordx4 v178, s[36:37]
	s_mov_b32 m0, s41
	s_nop 0
	global_load_lds_dwordx4 v182, s[36:37]
	s_waitcnt vmcnt(8)
	s_waitcnt lgkmcnt(0)
	s_barrier
	v_mfma_f32_16x16x32_bf16 v[126:129], v[130:133], v[162:165], v[126:129]
	v_mfma_f32_16x16x32_bf16 v[122:125], v[138:141], v[162:165], v[122:125]
	v_mfma_f32_16x16x32_bf16 v[110:113], v[130:133], v[170:173], v[110:113]
	v_mfma_f32_16x16x32_bf16 v[106:109], v[138:141], v[170:173], v[106:109]
	v_mfma_f32_16x16x32_bf16 v[94:97], v[130:133], v[194:197], v[94:97]
	v_mfma_f32_16x16x32_bf16 v[90:93], v[138:141], v[194:197], v[90:93]
	v_mfma_f32_16x16x32_bf16 v[78:81], v[130:133], v[204:207], v[78:81]
	v_mfma_f32_16x16x32_bf16 v[74:77], v[138:141], v[204:207], v[74:77]
	v_mfma_f32_16x16x32_bf16 v[126:129], v[134:137], v[166:169], v[126:129]
	v_mfma_f32_16x16x32_bf16 v[122:125], v[142:145], v[166:169], v[122:125]
	v_mfma_f32_16x16x32_bf16 v[110:113], v[134:137], v[174:177], v[110:113]
	v_mfma_f32_16x16x32_bf16 v[106:109], v[142:145], v[174:177], v[106:109]
	v_mfma_f32_16x16x32_bf16 v[94:97], v[134:137], v[200:203], v[94:97]
	v_mfma_f32_16x16x32_bf16 v[90:93], v[142:145], v[200:203], v[90:93]
	v_mfma_f32_16x16x32_bf16 v[78:81], v[134:137], v[214:217], v[78:81]
	v_mfma_f32_16x16x32_bf16 v[74:77], v[142:145], v[214:217], v[74:77]
	v_mfma_f32_16x16x32_bf16 v[118:121], v[146:149], v[162:165], v[118:121]
	v_mfma_f32_16x16x32_bf16 v[114:117], v[154:157], v[162:165], v[114:117]
	v_mfma_f32_16x16x32_bf16 v[102:105], v[146:149], v[170:173], v[102:105]
	v_mfma_f32_16x16x32_bf16 v[98:101], v[154:157], v[170:173], v[98:101]
	v_mfma_f32_16x16x32_bf16 v[86:89], v[146:149], v[194:197], v[86:89]
	v_mfma_f32_16x16x32_bf16 v[82:85], v[154:157], v[194:197], v[82:85]
	v_mfma_f32_16x16x32_bf16 v[70:73], v[146:149], v[204:207], v[70:73]
	v_mfma_f32_16x16x32_bf16 v[66:69], v[154:157], v[204:207], v[66:69]
	v_mfma_f32_16x16x32_bf16 v[118:121], v[150:153], v[166:169], v[118:121]
	v_mfma_f32_16x16x32_bf16 v[114:117], v[158:161], v[166:169], v[114:117]
	v_mfma_f32_16x16x32_bf16 v[102:105], v[150:153], v[174:177], v[102:105]
	v_mfma_f32_16x16x32_bf16 v[98:101], v[158:161], v[174:177], v[98:101]
	v_mfma_f32_16x16x32_bf16 v[86:89], v[150:153], v[200:203], v[86:89]
	v_mfma_f32_16x16x32_bf16 v[82:85], v[158:161], v[200:203], v[82:85]
	v_mfma_f32_16x16x32_bf16 v[70:73], v[150:153], v[214:217], v[70:73]
	v_mfma_f32_16x16x32_bf16 v[66:69], v[158:161], v[214:217], v[66:69]
	s_barrier
	s_add_i32 s36, s57, s38
	v_lshl_add_u64 v[208:209], v[208:209], 0, s[8:9]
	s_mov_b32 m0, s36
	ds_read_b128 v[162:165], v213 offset:49152
	ds_read_b128 v[166:169], v213 offset:50176
	ds_read_b128 v[170:173], v213 offset:51200
	ds_read_b128 v[174:177], v213 offset:52224
	ds_read_b128 v[194:197], v213 offset:53248
	ds_read_b128 v[200:203], v213 offset:54272
	ds_read_b128 v[204:207], v213 offset:55296
	ds_read_b128 v[214:217], v213 offset:56320
	global_load_lds_dwordx4 v[208:209], off
	s_add_i32 m0, s36, 0x2000
	s_add_u32 s34, s34, 0x80080
	v_lshl_add_u64 v[208:209], v[218:219], 0, s[8:9]
	s_addc_u32 s35, s35, 0
	s_add_i32 s36, s58, s38
	global_load_lds_dwordx4 v[208:209], off
	s_mov_b32 m0, s36
	s_nop 0
	global_load_lds_dwordx4 v180, s[34:35]
	s_add_i32 m0, s36, 0x2000
	s_nop 0
	global_load_lds_dwordx4 v184, s[34:35]
	s_waitcnt vmcnt(6)
	s_waitcnt lgkmcnt(0)
	s_barrier
	v_mfma_f32_16x16x32_bf16 v[62:65], v[130:133], v[162:165], v[62:65]
	v_mfma_f32_16x16x32_bf16 v[58:61], v[138:141], v[162:165], v[58:61]
	v_mfma_f32_16x16x32_bf16 v[46:49], v[130:133], v[170:173], v[46:49]
	v_mfma_f32_16x16x32_bf16 v[42:45], v[138:141], v[170:173], v[42:45]
	v_mfma_f32_16x16x32_bf16 v[30:33], v[130:133], v[194:197], v[30:33]
	v_mfma_f32_16x16x32_bf16 v[26:29], v[138:141], v[194:197], v[26:29]
	v_mfma_f32_16x16x32_bf16 v[14:17], v[130:133], v[204:207], v[14:17]
	v_mfma_f32_16x16x32_bf16 v[10:13], v[138:141], v[204:207], v[10:13]
	v_mfma_f32_16x16x32_bf16 v[62:65], v[134:137], v[166:169], v[62:65]
	v_mfma_f32_16x16x32_bf16 v[58:61], v[142:145], v[166:169], v[58:61]
	v_mfma_f32_16x16x32_bf16 v[46:49], v[134:137], v[174:177], v[46:49]
	v_mfma_f32_16x16x32_bf16 v[42:45], v[142:145], v[174:177], v[42:45]
	v_mfma_f32_16x16x32_bf16 v[30:33], v[134:137], v[200:203], v[30:33]
	v_mfma_f32_16x16x32_bf16 v[26:29], v[142:145], v[200:203], v[26:29]
	v_mfma_f32_16x16x32_bf16 v[14:17], v[134:137], v[214:217], v[14:17]
	v_mfma_f32_16x16x32_bf16 v[10:13], v[142:145], v[214:217], v[10:13]
	v_mfma_f32_16x16x32_bf16 v[54:57], v[146:149], v[162:165], v[54:57]
	v_mfma_f32_16x16x32_bf16 v[50:53], v[154:157], v[162:165], v[50:53]
	v_mfma_f32_16x16x32_bf16 v[38:41], v[146:149], v[170:173], v[38:41]
	v_mfma_f32_16x16x32_bf16 v[34:37], v[154:157], v[170:173], v[34:37]
	v_mfma_f32_16x16x32_bf16 v[22:25], v[146:149], v[194:197], v[22:25]
	v_mfma_f32_16x16x32_bf16 v[18:21], v[154:157], v[194:197], v[18:21]
	v_mfma_f32_16x16x32_bf16 v[6:9], v[146:149], v[204:207], v[6:9]
	v_mfma_f32_16x16x32_bf16 v[2:5], v[154:157], v[204:207], v[2:5]
	v_mfma_f32_16x16x32_bf16 v[54:57], v[150:153], v[166:169], v[54:57]
	v_mfma_f32_16x16x32_bf16 v[50:53], v[158:161], v[166:169], v[50:53]
	v_mfma_f32_16x16x32_bf16 v[38:41], v[150:153], v[174:177], v[38:41]
	v_mfma_f32_16x16x32_bf16 v[34:37], v[158:161], v[174:177], v[34:37]
	v_mfma_f32_16x16x32_bf16 v[22:25], v[150:153], v[200:203], v[22:25]
	v_mfma_f32_16x16x32_bf16 v[18:21], v[158:161], v[200:203], v[18:21]
	v_mfma_f32_16x16x32_bf16 v[6:9], v[150:153], v[214:217], v[6:9]
	v_mfma_f32_16x16x32_bf16 v[2:5], v[158:161], v[214:217], v[2:5]
	s_barrier
	s_add_i32 s56, s56, 2
	s_add_u32 s30, s30, 0x100
	s_addc_u32 s31, s31, 0
	s_add_u32 s52, s52, 0x100
	s_addc_u32 s53, s53, 0
	s_cmp_gt_u32 s56, 29
	s_cbranch_scc0 .LBB0_884
	s_and_b64 vcc, exec, s[10:11]
	s_cbranch_vccz .LBB0_887
	s_barrier

; #define PG8_STAGE(bufoff, gbase, voff) do { _Pragma("unroll") for (int _i = 0; _i < 2; ++_i) \
;         __builtin_amdgcn_global_load_lds((const unsigned*)((const char*)(gbase) + (voff)[_i]), (PG8_LAS unsigned*)(lds + (bufoff) + ldsw + _i * 8192), 16, 0, 0); } while (0)
; #define PG8_LDA(dst, b, h) do { _Pragma("unroll") for (int m = 0; m < 4; ++m) _Pragma("unroll") for (int k = 0; k < 2; ++k) dst[m][k] = *(const PG8_LAS bf16x8*)(lds + PG8_SA(b, h) + aoff + m * 2048 + k * 1024); } while (0)
; #define PG8_LDB(dst, b, h) do { _Pragma("unroll") for (int n = 0; n < 2; ++n) _Pragma("unroll") for (int k = 0; k < 2; ++k) dst[n][k] = *(const PG8_LAS bf16x8*)(lds + PG8_SB(b, h) + boff + n * 2048 + k * 1024); } while (0)
; #define PG8_MMA(ai, bj, At, Bt) do { __builtin_amdgcn_s_setprio(1); _Pragma("unroll") for (int m = 0; m < 4; ++m) _Pragma("unroll") for (int n = 0; n < 2; ++n) _Pragma("unroll") for (int k = 0; k < 2; ++k) \
;         acc[ai][bj][m][n] = __builtin_amdgcn_mfma_f32_16x16x32_bf16(Bt[n][k], At[m][k], acc[ai][bj][m][n], 0, 0, 0); __builtin_amdgcn_s_setprio(0); } while (0)
; #define PG8_WAIT_V(n) asm volatile("s_waitcnt vmcnt(" #n ")" ::: "memory")
; #define PG8_BAR __builtin_amdgcn_s_barrier()
; template <class Epi, class Sched, bool ALIGN_EPI = false, bool SP2 = false>
; __device__ __forceinline__ void gemm_phase(PG8_LAS unsigned char* lds, const Gemm g, const Sched& S, const Epi& E) {
;     ...
;         for (int t = 0; t < nt; t += 2) {
;             const bool last = (t == nt - 2);
;             const char* a1 = cA + (size_t)(t + 1) * kstep;
;             const char* a2 = last ? nA : cA + (size_t)(t + 2) * kstep; const char* b2 = last ? nB : cB + (size_t)(t + 2) * kstep;
;             const char* a3 = a2 + kstep; const char* b3 = b2 + kstep;
;             if (last && has_next) S.a_ready(nxt);
;             if constexpr (SP2) {
;             PG8_LDB(B0, 0, 0); PG8_LDB(B1, 0, 1); PG8_SCHED; PG8_LDA(At, 0, 0); PG8_STAGE(PG8_SA(1, 1), a1 + hstep, voffA);
;             PG8_WAIT_V(8); PG8_WAIT_L(0); PG8_BAR; PG8_MMA(0, 0, At, B0); PG8_MMA(0, 1, At, B1); PG8_BAR; PG8_SCHED;
;             PG8_LDA(At, 0, 1); PG8_STAGE(PG8_SB(0, 0), b2, voffB); PG8_STAGE(PG8_SB(0, 1), b2 + hstep, voffB); PG8_STAGE(PG8_SA(0, 0), a2, voffA);
;             PG8_WAIT_V(8); PG8_WAIT_L(0); PG8_BAR; PG8_MMA(1, 0, At, B0); PG8_MMA(1, 1, At, B1); PG8_BAR; PG8_SCHED;
.LBB0_959:
	s_add_u32 s30, s28, 0xfff00000
	s_addc_u32 s31, s29, -1
	s_mov_b32 m0, s41
	s_nop 0
	global_load_lds_dwordx4 v138, s[30:31]
	s_mov_b32 m0, s42
	s_nop 0
	global_load_lds_dwordx4 v142, s[30:31]
	s_add_u32 s30, s30, 0x80
	s_addc_u32 s31, s31, 0
	ds_read_b128 v[130:133], v164
	ds_read_b128 v[134:137], v164 offset:1024
	ds_read_b128 v[154:157], v164 offset:2048
	ds_read_b128 v[158:161], v164 offset:3072
	ds_read_b128 v[168:171], v165
	ds_read_b128 v[172:175], v165 offset:1024
	ds_read_b128 v[176:179], v165 offset:2048
	ds_read_b128 v[180:183], v165 offset:3072
	s_cmp_eq_u32 s51, 60
	s_cselect_b32 s35, s13, s31
	s_cselect_b32 s34, s47, s30
	s_cselect_b32 s31, s11, s50
	s_cselect_b32 s30, s48, s49
	s_add_i32 m0, s27, 0xc000
	ds_read_b128 v[184:187], v166
	ds_read_b128 v[188:191], v166 offset:1024
	ds_read_b128 v[192:195], v166 offset:2048
	ds_read_b128 v[200:203], v166 offset:3072
	ds_read_b128 v[204:207], v166 offset:4096
	ds_read_b128 v[208:211], v166 offset:5120
	ds_read_b128 v[212:215], v166 offset:6144
	ds_read_b128 v[216:219], v166 offset:7168
	global_load_lds_dwordx4 v146, s[28:29]
	s_add_i32 m0, s27, 0xe000
	s_nop 0
	global_load_lds_dwordx4 v148, s[28:29]
	s_waitcnt vmcnt(8)
	s_waitcnt lgkmcnt(0)
	s_barrier
	v_mfma_f32_16x16x32_bf16 v[126:129], v[130:133], v[184:187], v[126:129]
	v_mfma_f32_16x16x32_bf16 v[122:125], v[154:157], v[184:187], v[122:125]
	v_mfma_f32_16x16x32_bf16 v[118:121], v[130:133], v[192:195], v[118:121]
	v_mfma_f32_16x16x32_bf16 v[114:117], v[154:157], v[192:195], v[114:117]
	v_mfma_f32_16x16x32_bf16 v[110:113], v[130:133], v[204:207], v[110:113]
	v_mfma_f32_16x16x32_bf16 v[102:105], v[154:157], v[204:207], v[102:105]
	v_mfma_f32_16x16x32_bf16 v[82:85], v[130:133], v[212:215], v[82:85]
	v_mfma_f32_16x16x32_bf16 v[74:77], v[154:157], v[212:215], v[74:77]
	v_mfma_f32_16x16x32_bf16 v[126:129], v[134:137], v[188:191], v[126:129]
	v_mfma_f32_16x16x32_bf16 v[122:125], v[158:161], v[188:191], v[122:125]
	v_mfma_f32_16x16x32_bf16 v[118:121], v[134:137], v[200:203], v[118:121]
	v_mfma_f32_16x16x32_bf16 v[114:117], v[158:161], v[200:203], v[114:117]
	v_mfma_f32_16x16x32_bf16 v[110:113], v[134:137], v[208:211], v[110:113]
	v_mfma_f32_16x16x32_bf16 v[102:105], v[158:161], v[208:211], v[102:105]
	v_mfma_f32_16x16x32_bf16 v[82:85], v[134:137], v[216:219], v[82:85]
	v_mfma_f32_16x16x32_bf16 v[74:77], v[158:161], v[216:219], v[74:77]
	v_mfma_f32_16x16x32_bf16 v[106:109], v[168:171], v[184:187], v[106:109]
	v_mfma_f32_16x16x32_bf16 v[98:101], v[176:179], v[184:187], v[98:101]
	v_mfma_f32_16x16x32_bf16 v[94:97], v[168:171], v[192:195], v[94:97]
	v_mfma_f32_16x16x32_bf16 v[90:93], v[176:179], v[192:195], v[90:93]
	v_mfma_f32_16x16x32_bf16 v[86:89], v[168:171], v[204:207], v[86:89]
	v_mfma_f32_16x16x32_bf16 v[78:81], v[176:179], v[204:207], v[78:81]
	v_mfma_f32_16x16x32_bf16 v[70:73], v[168:171], v[212:215], v[70:73]
	v_mfma_f32_16x16x32_bf16 v[66:69], v[176:179], v[212:215], v[66:69]
	v_mfma_f32_16x16x32_bf16 v[106:109], v[172:175], v[188:191], v[106:109]
	v_mfma_f32_16x16x32_bf16 v[98:101], v[180:183], v[188:191], v[98:101]
	v_mfma_f32_16x16x32_bf16 v[94:97], v[172:175], v[200:203], v[94:97]
	v_mfma_f32_16x16x32_bf16 v[90:93], v[180:183], v[200:203], v[90:93]
	v_mfma_f32_16x16x32_bf16 v[86:89], v[172:175], v[208:211], v[86:89]
	v_mfma_f32_16x16x32_bf16 v[78:81], v[180:183], v[208:211], v[78:81]
	v_mfma_f32_16x16x32_bf16 v[70:73], v[172:175], v[216:219], v[70:73]
	v_mfma_f32_16x16x32_bf16 v[66:69], v[180:183], v[216:219], v[66:69]
	s_barrier
	s_add_i32 s52, s44, s36
	v_lshl_add_u64 v[196:197], s[30:31], 0, v[140:141]
	s_mov_b32 m0, s52
	ds_read_b128 v[184:187], v166 offset:16384
	ds_read_b128 v[188:191], v166 offset:17408
	ds_read_b128 v[192:195], v166 offset:18432
	ds_read_b128 v[200:203], v166 offset:19456
	ds_read_b128 v[204:207], v166 offset:20480
	ds_read_b128 v[208:211], v166 offset:21504
	ds_read_b128 v[212:215], v166 offset:22528
	ds_read_b128 v[216:219], v166 offset:23552
	global_load_lds_dwordx4 v140, s[30:31]
	s_add_i32 m0, s52, 0x2000
	s_add_u32 s52, s30, 0x100000
	v_lshl_add_u64 v[220:221], s[30:31], 0, v[144:145]
	s_addc_u32 s53, s31, 0
	s_add_i32 s54, s45, s36
	global_load_lds_dwordx4 v144, s[30:31]
	s_mov_b32 m0, s54
	s_nop 0
	global_load_lds_dwordx4 v140, s[52:53]
	s_add_i32 m0, s54, 0x2000
	s_nop 0
	global_load_lds_dwordx4 v144, s[52:53]
	s_waitcnt vmcnt(6)
	s_waitcnt lgkmcnt(0)
	s_barrier
	v_mfma_f32_16x16x32_bf16 v[62:65], v[130:133], v[184:187], v[62:65]
	v_mfma_f32_16x16x32_bf16 v[58:61], v[154:157], v[184:187], v[58:61]
	v_mfma_f32_16x16x32_bf16 v[50:53], v[130:133], v[192:195], v[50:53]
	v_mfma_f32_16x16x32_bf16 v[42:45], v[154:157], v[192:195], v[42:45]
	v_mfma_f32_16x16x32_bf16 v[34:37], v[130:133], v[204:207], v[34:37]
	v_mfma_f32_16x16x32_bf16 v[26:29], v[154:157], v[204:207], v[26:29]
	v_mfma_f32_16x16x32_bf16 v[18:21], v[130:133], v[212:215], v[18:21]
	v_mfma_f32_16x16x32_bf16 v[10:13], v[154:157], v[212:215], v[10:13]
	v_mfma_f32_16x16x32_bf16 v[62:65], v[134:137], v[188:191], v[62:65]
	v_mfma_f32_16x16x32_bf16 v[58:61], v[158:161], v[188:191], v[58:61]
	v_mfma_f32_16x16x32_bf16 v[50:53], v[134:137], v[200:203], v[50:53]
	v_mfma_f32_16x16x32_bf16 v[42:45], v[158:161], v[200:203], v[42:45]
	v_mfma_f32_16x16x32_bf16 v[34:37], v[134:137], v[208:211], v[34:37]
	v_mfma_f32_16x16x32_bf16 v[26:29], v[158:161], v[208:211], v[26:29]
	v_mfma_f32_16x16x32_bf16 v[18:21], v[134:137], v[216:219], v[18:21]
	v_mfma_f32_16x16x32_bf16 v[10:13], v[158:161], v[216:219], v[10:13]
	v_mfma_f32_16x16x32_bf16 v[54:57], v[168:171], v[184:187], v[54:57]
	v_mfma_f32_16x16x32_bf16 v[46:49], v[176:179], v[184:187], v[46:49]
	v_mfma_f32_16x16x32_bf16 v[38:41], v[168:171], v[192:195], v[38:41]
	v_mfma_f32_16x16x32_bf16 v[30:33], v[176:179], v[192:195], v[30:33]
	v_mfma_f32_16x16x32_bf16 v[22:25], v[168:171], v[204:207], v[22:25]
	v_mfma_f32_16x16x32_bf16 v[14:17], v[176:179], v[204:207], v[14:17]
	v_mfma_f32_16x16x32_bf16 v[6:9], v[168:171], v[212:215], v[6:9]
	v_mfma_f32_16x16x32_bf16 v[2:5], v[176:179], v[212:215], v[2:5]
	v_mfma_f32_16x16x32_bf16 v[54:57], v[172:175], v[188:191], v[54:57]
	v_mfma_f32_16x16x32_bf16 v[46:49], v[180:183], v[188:191], v[46:49]
	v_mfma_f32_16x16x32_bf16 v[38:41], v[172:175], v[200:203], v[38:41]
	v_mfma_f32_16x16x32_bf16 v[30:33], v[180:183], v[200:203], v[30:33]
	v_mfma_f32_16x16x32_bf16 v[22:25], v[172:175], v[208:211], v[22:25]
	v_mfma_f32_16x16x32_bf16 v[14:17], v[180:183], v[208:211], v[14:17]
	v_mfma_f32_16x16x32_bf16 v[6:9], v[172:175], v[216:219], v[6:9]
	v_mfma_f32_16x16x32_bf16 v[2:5], v[180:183], v[216:219], v[2:5]
	s_barrier
; #define PG8_STAGE(bufoff, gbase, voff) do { _Pragma("unroll") for (int _i = 0; _i < 2; ++_i) \
;         __builtin_amdgcn_global_load_lds((const unsigned*)((const char*)(gbase) + (voff)[_i]), (PG8_LAS unsigned*)(lds + (bufoff) + ldsw + _i * 8192), 16, 0, 0); } while (0)
; #define PG8_LDA(dst, b, h) do { _Pragma("unroll") for (int m = 0; m < 4; ++m) _Pragma("unroll") for (int k = 0; k < 2; ++k) dst[m][k] = *(const PG8_LAS bf16x8*)(lds + PG8_SA(b, h) + aoff + m * 2048 + k * 1024); } while (0)
; #define PG8_LDB(dst, b, h) do { _Pragma("unroll") for (int n = 0; n < 2; ++n) _Pragma("unroll") for (int k = 0; k < 2; ++k) dst[n][k] = *(const PG8_LAS bf16x8*)(lds + PG8_SB(b, h) + boff + n * 2048 + k * 1024); } while (0)
; #define PG8_MMA(ai, bj, At, Bt) do { __builtin_amdgcn_s_setprio(1); _Pragma("unroll") for (int m = 0; m < 4; ++m) _Pragma("unroll") for (int n = 0; n < 2; ++n) _Pragma("unroll") for (int k = 0; k < 2; ++k) \
;         acc[ai][bj][m][n] = __builtin_amdgcn_mfma_f32_16x16x32_bf16(Bt[n][k], At[m][k], acc[ai][bj][m][n], 0, 0, 0); __builtin_amdgcn_s_setprio(0); } while (0)
; #define PG8_WAIT_V(n) asm volatile("s_waitcnt vmcnt(" #n ")" ::: "memory")
; #define PG8_WAIT_L(n) asm volatile("s_waitcnt lgkmcnt(" #n ")" ::: "memory")
; #define PG8_BAR __builtin_amdgcn_s_barrier()
; #define PG8_SCHED __builtin_amdgcn_sched_barrier(0)
; template <class Epi, class Sched, bool ALIGN_EPI = false, bool SP2 = false>
; __device__ __forceinline__ void gemm_phase(PG8_LAS unsigned char* lds, const Gemm g, const Sched& S, const Epi& E) {
;     ...
;             PG8_LDB(B0, 1, 0); PG8_LDB(B1, 1, 1); PG8_SCHED; PG8_LDA(At, 1, 0); PG8_STAGE(PG8_SA(0, 1), a2 + hstep, voffA);
;             PG8_WAIT_V(8); PG8_WAIT_L(0); PG8_BAR; PG8_MMA(0, 0, At, B0); PG8_MMA(0, 1, At, B1); PG8_BAR; PG8_SCHED;
;             PG8_LDA(At, 1, 1); PG8_STAGE(PG8_SB(1, 0), b3, voffB); PG8_STAGE(PG8_SB(1, 1), b3 + hstep, voffB); PG8_STAGE(PG8_SA(1, 0), a3, voffA);
;             PG8_WAIT_V(8); PG8_WAIT_L(0); PG8_BAR; PG8_MMA(1, 0, At, B0); PG8_MMA(1, 1, At, B1); PG8_BAR; PG8_SCHED;
	s_mov_b32 m0, s27
	s_nop 0
	global_load_lds_dwordx4 v138, s[34:35]
	s_mov_b32 m0, s37
	s_nop 0
	global_load_lds_dwordx4 v142, s[34:35]
	s_add_i32 s52, 0, 0x18000
	s_add_i32 s53, 0, 0x1c000
	v_add_u32_e32 v158, s52, v162
	v_add_u32_e32 v167, s53, v162
	ds_read_b128 v[130:133], v158
	ds_read_b128 v[134:137], v158 offset:1024
	ds_read_b128 v[154:157], v158 offset:2048
	ds_read_b128 v[158:161], v158 offset:3072
	ds_read_b128 v[168:171], v167
	ds_read_b128 v[172:175], v167 offset:1024
	ds_read_b128 v[176:179], v167 offset:2048
	ds_read_b128 v[180:183], v167 offset:3072
	s_add_u32 s34, s34, 0x100000
	s_addc_u32 s35, s35, 0
	s_mov_b32 m0, s38
	ds_read_b128 v[184:187], v166 offset:32768
	ds_read_b128 v[188:191], v166 offset:33792
	ds_read_b128 v[192:195], v166 offset:34816
	ds_read_b128 v[200:203], v166 offset:35840
	ds_read_b128 v[204:207], v166 offset:36864
	ds_read_b128 v[208:211], v166 offset:37888
	ds_read_b128 v[212:215], v166 offset:38912
	ds_read_b128 v[216:219], v166 offset:39936
	global_load_lds_dwordx4 v138, s[34:35]
	s_mov_b32 m0, s39
	s_nop 0
	global_load_lds_dwordx4 v142, s[34:35]
	s_waitcnt vmcnt(8)
	s_waitcnt lgkmcnt(0)
	s_barrier
	v_mfma_f32_16x16x32_bf16 v[126:129], v[130:133], v[184:187], v[126:129]
	v_mfma_f32_16x16x32_bf16 v[122:125], v[154:157], v[184:187], v[122:125]
	v_mfma_f32_16x16x32_bf16 v[118:121], v[130:133], v[192:195], v[118:121]
	v_mfma_f32_16x16x32_bf16 v[114:117], v[154:157], v[192:195], v[114:117]
	v_mfma_f32_16x16x32_bf16 v[110:113], v[130:133], v[204:207], v[110:113]
	v_mfma_f32_16x16x32_bf16 v[102:105], v[154:157], v[204:207], v[102:105]
	v_mfma_f32_16x16x32_bf16 v[82:85], v[130:133], v[212:215], v[82:85]
	v_mfma_f32_16x16x32_bf16 v[74:77], v[154:157], v[212:215], v[74:77]
	v_mfma_f32_16x16x32_bf16 v[126:129], v[134:137], v[188:191], v[126:129]
	v_mfma_f32_16x16x32_bf16 v[122:125], v[158:161], v[188:191], v[122:125]
	v_mfma_f32_16x16x32_bf16 v[118:121], v[134:137], v[200:203], v[118:121]
	v_mfma_f32_16x16x32_bf16 v[114:117], v[158:161], v[200:203], v[114:117]
	v_mfma_f32_16x16x32_bf16 v[110:113], v[134:137], v[208:211], v[110:113]
	v_mfma_f32_16x16x32_bf16 v[102:105], v[158:161], v[208:211], v[102:105]
	v_mfma_f32_16x16x32_bf16 v[82:85], v[134:137], v[216:219], v[82:85]
	v_mfma_f32_16x16x32_bf16 v[74:77], v[158:161], v[216:219], v[74:77]
	v_mfma_f32_16x16x32_bf16 v[106:109], v[168:171], v[184:187], v[106:109]
	v_mfma_f32_16x16x32_bf16 v[98:101], v[176:179], v[184:187], v[98:101]
	v_mfma_f32_16x16x32_bf16 v[94:97], v[168:171], v[192:195], v[94:97]
	v_mfma_f32_16x16x32_bf16 v[90:93], v[176:179], v[192:195], v[90:93]
	v_mfma_f32_16x16x32_bf16 v[86:89], v[168:171], v[204:207], v[86:89]
	v_mfma_f32_16x16x32_bf16 v[78:81], v[176:179], v[204:207], v[78:81]
	v_mfma_f32_16x16x32_bf16 v[70:73], v[168:171], v[212:215], v[70:73]
	v_mfma_f32_16x16x32_bf16 v[66:69], v[176:179], v[212:215], v[66:69]
	v_mfma_f32_16x16x32_bf16 v[106:109], v[172:175], v[188:191], v[106:109]
	v_mfma_f32_16x16x32_bf16 v[98:101], v[180:183], v[188:191], v[98:101]
	v_mfma_f32_16x16x32_bf16 v[94:97], v[172:175], v[200:203], v[94:97]
	v_mfma_f32_16x16x32_bf16 v[90:93], v[180:183], v[200:203], v[90:93]
	v_mfma_f32_16x16x32_bf16 v[86:89], v[172:175], v[208:211], v[86:89]
	v_mfma_f32_16x16x32_bf16 v[78:81], v[180:183], v[208:211], v[78:81]
	v_mfma_f32_16x16x32_bf16 v[70:73], v[172:175], v[216:219], v[70:73]
	v_mfma_f32_16x16x32_bf16 v[66:69], v[180:183], v[216:219], v[66:69]
	s_barrier
	s_add_i32 s34, s52, s36
	v_lshl_add_u64 v[196:197], v[196:197], 0, s[6:7]
	s_mov_b32 m0, s34
	ds_read_b128 v[184:187], v166 offset:49152
	ds_read_b128 v[188:191], v166 offset:50176
	ds_read_b128 v[192:195], v166 offset:51200
	ds_read_b128 v[200:203], v166 offset:52224
	ds_read_b128 v[204:207], v166 offset:53248
	ds_read_b128 v[208:211], v166 offset:54272
	ds_read_b128 v[212:215], v166 offset:55296
	ds_read_b128 v[216:219], v166 offset:56320
	global_load_lds_dwordx4 v[196:197], off
	s_add_i32 m0, s34, 0x2000
	s_add_u32 s30, s30, 0x100080
	v_lshl_add_u64 v[196:197], v[220:221], 0, s[6:7]
	s_addc_u32 s31, s31, 0
	s_add_i32 s34, s53, s36
	global_load_lds_dwordx4 v[196:197], off
	s_mov_b32 m0, s34
	s_nop 0
	global_load_lds_dwordx4 v140, s[30:31]
	s_add_i32 m0, s34, 0x2000
	s_nop 0
	global_load_lds_dwordx4 v144, s[30:31]
	s_waitcnt vmcnt(6)
	s_waitcnt lgkmcnt(0)
	s_barrier
	v_mfma_f32_16x16x32_bf16 v[62:65], v[130:133], v[184:187], v[62:65]
	v_mfma_f32_16x16x32_bf16 v[58:61], v[154:157], v[184:187], v[58:61]
	v_mfma_f32_16x16x32_bf16 v[50:53], v[130:133], v[192:195], v[50:53]
	v_mfma_f32_16x16x32_bf16 v[42:45], v[154:157], v[192:195], v[42:45]
	v_mfma_f32_16x16x32_bf16 v[34:37], v[130:133], v[204:207], v[34:37]
	v_mfma_f32_16x16x32_bf16 v[26:29], v[154:157], v[204:207], v[26:29]
	v_mfma_f32_16x16x32_bf16 v[18:21], v[130:133], v[212:215], v[18:21]
	v_mfma_f32_16x16x32_bf16 v[10:13], v[154:157], v[212:215], v[10:13]
	v_mfma_f32_16x16x32_bf16 v[62:65], v[134:137], v[188:191], v[62:65]
	v_mfma_f32_16x16x32_bf16 v[58:61], v[158:161], v[188:191], v[58:61]
	v_mfma_f32_16x16x32_bf16 v[50:53], v[134:137], v[200:203], v[50:53]
	v_mfma_f32_16x16x32_bf16 v[42:45], v[158:161], v[200:203], v[42:45]
	v_mfma_f32_16x16x32_bf16 v[34:37], v[134:137], v[208:211], v[34:37]
	v_mfma_f32_16x16x32_bf16 v[26:29], v[158:161], v[208:211], v[26:29]
	v_mfma_f32_16x16x32_bf16 v[18:21], v[134:137], v[216:219], v[18:21]
	v_mfma_f32_16x16x32_bf16 v[10:13], v[158:161], v[216:219], v[10:13]
	v_mfma_f32_16x16x32_bf16 v[54:57], v[168:171], v[184:187], v[54:57]
	v_mfma_f32_16x16x32_bf16 v[46:49], v[176:179], v[184:187], v[46:49]
	v_mfma_f32_16x16x32_bf16 v[38:41], v[168:171], v[192:195], v[38:41]
	v_mfma_f32_16x16x32_bf16 v[30:33], v[176:179], v[192:195], v[30:33]
	v_mfma_f32_16x16x32_bf16 v[22:25], v[168:171], v[204:207], v[22:25]
	v_mfma_f32_16x16x32_bf16 v[14:17], v[176:179], v[204:207], v[14:17]
	v_mfma_f32_16x16x32_bf16 v[6:9], v[168:171], v[212:215], v[6:9]
	v_mfma_f32_16x16x32_bf16 v[2:5], v[176:179], v[212:215], v[2:5]
	v_mfma_f32_16x16x32_bf16 v[54:57], v[172:175], v[188:191], v[54:57]
	v_mfma_f32_16x16x32_bf16 v[46:49], v[180:183], v[188:191], v[46:49]
	v_mfma_f32_16x16x32_bf16 v[38:41], v[172:175], v[200:203], v[38:41]
	v_mfma_f32_16x16x32_bf16 v[30:33], v[180:183], v[200:203], v[30:33]
	v_mfma_f32_16x16x32_bf16 v[22:25], v[172:175], v[208:211], v[22:25]
	v_mfma_f32_16x16x32_bf16 v[14:17], v[180:183], v[208:211], v[14:17]
	v_mfma_f32_16x16x32_bf16 v[6:9], v[172:175], v[216:219], v[6:9]
	v_mfma_f32_16x16x32_bf16 v[2:5], v[180:183], v[216:219], v[2:5]
	s_barrier
	s_add_i32 s51, s51, 2
	s_add_u32 s28, s28, 0x100
	s_addc_u32 s29, s29, 0
	s_add_u32 s49, s49, 0x100
	s_addc_u32 s50, s50, 0
	s_cmp_gt_u32 s51, 61
	s_cbranch_scc0 .LBB0_959
	s_and_b64 vcc, exec, s[8:9]
	s_cbranch_vccz .LBB0_962
	s_barrier

; #define PG8_STAGE(bufoff, gbase, voff) do { _Pragma("unroll") for (int _i = 0; _i < 2; ++_i) \
;         __builtin_amdgcn_global_load_lds((const unsigned*)((const char*)(gbase) + (voff)[_i]), (PG8_LAS unsigned*)(lds + (bufoff) + ldsw + _i * 8192), 16, 0, 0); } while (0)
; #define PG8_LDA(dst, b, h) do { _Pragma("unroll") for (int m = 0; m < 4; ++m) _Pragma("unroll") for (int k = 0; k < 2; ++k) dst[m][k] = *(const PG8_LAS bf16x8*)(lds + PG8_SA(b, h) + aoff + m * 2048 + k * 1024); } while (0)
; #define PG8_LDB(dst, b, h) do { _Pragma("unroll") for (int n = 0; n < 2; ++n) _Pragma("unroll") for (int k = 0; k < 2; ++k) dst[n][k] = *(const PG8_LAS bf16x8*)(lds + PG8_SB(b, h) + boff + n * 2048 + k * 1024); } while (0)
; #define PG8_MMA(ai, bj, At, Bt) do { __builtin_amdgcn_s_setprio(1); _Pragma("unroll") for (int m = 0; m < 4; ++m) _Pragma("unroll") for (int n = 0; n < 2; ++n) _Pragma("unroll") for (int k = 0; k < 2; ++k) \
;         acc[ai][bj][m][n] = __builtin_amdgcn_mfma_f32_16x16x32_bf16(Bt[n][k], At[m][k], acc[ai][bj][m][n], 0, 0, 0); __builtin_amdgcn_s_setprio(0); } while (0)
; #define PG8_WAIT_V(n) asm volatile("s_waitcnt vmcnt(" #n ")" ::: "memory")
; #define PG8_BAR __builtin_amdgcn_s_barrier()
; template <class Epi, class Sched, bool ALIGN_EPI = false, bool SP2 = false>
; __device__ __forceinline__ void gemm_phase(PG8_LAS unsigned char* lds, const Gemm g, const Sched& S, const Epi& E) {
;     ...
;         for (int t = 0; t < nt; t += 2) {
;             const bool last = (t == nt - 2);
;             const char* a1 = cA + (size_t)(t + 1) * kstep;
;             const char* a2 = last ? nA : cA + (size_t)(t + 2) * kstep; const char* b2 = last ? nB : cB + (size_t)(t + 2) * kstep;
;             const char* a3 = a2 + kstep; const char* b3 = b2 + kstep;
;             if (last && has_next) S.a_ready(nxt);
;             if constexpr (SP2) {
;             PG8_LDB(B0, 0, 0); PG8_LDB(B1, 0, 1); PG8_SCHED; PG8_LDA(At, 0, 0); PG8_STAGE(PG8_SA(1, 1), a1 + hstep, voffA);
;             PG8_WAIT_V(8); PG8_WAIT_L(0); PG8_BAR; PG8_MMA(0, 0, At, B0); PG8_MMA(0, 1, At, B1); PG8_BAR; PG8_SCHED;
;             PG8_LDA(At, 0, 1); PG8_STAGE(PG8_SB(0, 0), b2, voffB); PG8_STAGE(PG8_SB(0, 1), b2 + hstep, voffB); PG8_STAGE(PG8_SA(0, 0), a2, voffA);
;             PG8_WAIT_V(8); PG8_WAIT_L(0); PG8_BAR; PG8_MMA(1, 0, At, B0); PG8_MMA(1, 1, At, B1); PG8_BAR; PG8_SCHED;
.LBB0_1081:
	s_add_u32 s34, s30, 0xfff00000
	s_addc_u32 s35, s31, -1
	s_mov_b32 m0, s44
	s_nop 0
	global_load_lds_dwordx4 v136, s[34:35]
	s_mov_b32 m0, s45
	s_nop 0
	global_load_lds_dwordx4 v132, s[34:35]
	s_add_u32 s34, s34, 0x80
	s_addc_u32 s35, s35, 0
	ds_read_b128 v[154:157], v150
	ds_read_b128 v[158:161], v150 offset:1024
	ds_read_b128 v[162:165], v150 offset:2048
	ds_read_b128 v[166:169], v150 offset:3072
	ds_read_b128 v[170:173], v151
	ds_read_b128 v[174:177], v151 offset:1024
	ds_read_b128 v[178:181], v151 offset:2048
	ds_read_b128 v[182:185], v151 offset:3072
	s_cmp_eq_u32 s55, 60
	s_cselect_b32 s37, s15, s35
	s_cselect_b32 s36, s51, s34
	s_cselect_b32 s35, s13, s54
	s_cselect_b32 s34, s52, s53
	s_add_i32 m0, s29, 0xc000
	ds_read_b128 v[186:189], v152
	ds_read_b128 v[190:193], v152 offset:1024
	ds_read_b128 v[194:197], v152 offset:2048
	ds_read_b128 v[200:203], v152 offset:3072
	ds_read_b128 v[204:207], v152 offset:4096
	ds_read_b128 v[208:211], v152 offset:5120
	ds_read_b128 v[212:215], v152 offset:6144
	ds_read_b128 v[216:219], v152 offset:7168
	global_load_lds_dwordx4 v138, s[30:31]
	s_add_i32 m0, s29, 0xe000
	s_nop 0
	global_load_lds_dwordx4 v140, s[30:31]
	s_waitcnt vmcnt(8)
	s_waitcnt lgkmcnt(0)
	s_barrier
	v_mfma_f32_16x16x32_bf16 v[126:129], v[154:157], v[186:189], v[126:129]
	v_mfma_f32_16x16x32_bf16 v[122:125], v[162:165], v[186:189], v[122:125]
	v_mfma_f32_16x16x32_bf16 v[110:113], v[154:157], v[194:197], v[110:113]
	v_mfma_f32_16x16x32_bf16 v[106:109], v[162:165], v[194:197], v[106:109]
	v_mfma_f32_16x16x32_bf16 v[94:97], v[154:157], v[204:207], v[94:97]
	v_mfma_f32_16x16x32_bf16 v[90:93], v[162:165], v[204:207], v[90:93]
	v_mfma_f32_16x16x32_bf16 v[78:81], v[154:157], v[212:215], v[78:81]
	v_mfma_f32_16x16x32_bf16 v[74:77], v[162:165], v[212:215], v[74:77]
	v_mfma_f32_16x16x32_bf16 v[126:129], v[158:161], v[190:193], v[126:129]
	v_mfma_f32_16x16x32_bf16 v[122:125], v[166:169], v[190:193], v[122:125]
	v_mfma_f32_16x16x32_bf16 v[110:113], v[158:161], v[200:203], v[110:113]
	v_mfma_f32_16x16x32_bf16 v[106:109], v[166:169], v[200:203], v[106:109]
	v_mfma_f32_16x16x32_bf16 v[94:97], v[158:161], v[208:211], v[94:97]
	v_mfma_f32_16x16x32_bf16 v[90:93], v[166:169], v[208:211], v[90:93]
	v_mfma_f32_16x16x32_bf16 v[78:81], v[158:161], v[216:219], v[78:81]
	v_mfma_f32_16x16x32_bf16 v[74:77], v[166:169], v[216:219], v[74:77]
	v_mfma_f32_16x16x32_bf16 v[118:121], v[170:173], v[186:189], v[118:121]
	v_mfma_f32_16x16x32_bf16 v[114:117], v[178:181], v[186:189], v[114:117]
	v_mfma_f32_16x16x32_bf16 v[102:105], v[170:173], v[194:197], v[102:105]
	v_mfma_f32_16x16x32_bf16 v[98:101], v[178:181], v[194:197], v[98:101]
	v_mfma_f32_16x16x32_bf16 v[86:89], v[170:173], v[204:207], v[86:89]
	v_mfma_f32_16x16x32_bf16 v[82:85], v[178:181], v[204:207], v[82:85]
	v_mfma_f32_16x16x32_bf16 v[70:73], v[170:173], v[212:215], v[70:73]
	v_mfma_f32_16x16x32_bf16 v[66:69], v[178:181], v[212:215], v[66:69]
	v_mfma_f32_16x16x32_bf16 v[118:121], v[174:177], v[190:193], v[118:121]
	v_mfma_f32_16x16x32_bf16 v[114:117], v[182:185], v[190:193], v[114:117]
	v_mfma_f32_16x16x32_bf16 v[102:105], v[174:177], v[200:203], v[102:105]
	v_mfma_f32_16x16x32_bf16 v[98:101], v[182:185], v[200:203], v[98:101]
	v_mfma_f32_16x16x32_bf16 v[86:89], v[174:177], v[208:211], v[86:89]
	v_mfma_f32_16x16x32_bf16 v[82:85], v[182:185], v[208:211], v[82:85]
	v_mfma_f32_16x16x32_bf16 v[70:73], v[174:177], v[216:219], v[70:73]
	v_mfma_f32_16x16x32_bf16 v[66:69], v[182:185], v[216:219], v[66:69]
	s_barrier
	s_add_i32 s56, s47, s33
	v_lshl_add_u64 v[146:147], s[34:35], 0, v[134:135]
	s_mov_b32 m0, s56
	ds_read_b128 v[186:189], v152 offset:16384
	ds_read_b128 v[190:193], v152 offset:17408
	ds_read_b128 v[194:197], v152 offset:18432
	ds_read_b128 v[200:203], v152 offset:19456
	ds_read_b128 v[204:207], v152 offset:20480
	ds_read_b128 v[208:211], v152 offset:21504
	ds_read_b128 v[212:215], v152 offset:22528
	ds_read_b128 v[216:219], v152 offset:23552
	global_load_lds_dwordx4 v134, s[34:35]
	s_add_i32 m0, s56, 0x2000
	s_add_u32 s56, s34, 0x100000
	v_lshl_add_u64 v[220:221], s[34:35], 0, v[130:131]
	s_addc_u32 s57, s35, 0
	s_add_i32 s58, s48, s33
	global_load_lds_dwordx4 v130, s[34:35]
	s_mov_b32 m0, s58
	s_nop 0
	global_load_lds_dwordx4 v134, s[56:57]
	s_add_i32 m0, s58, 0x2000
	s_nop 0
	global_load_lds_dwordx4 v130, s[56:57]
	s_waitcnt vmcnt(6)
	s_waitcnt lgkmcnt(0)
	s_barrier
	v_mfma_f32_16x16x32_bf16 v[62:65], v[154:157], v[186:189], v[62:65]
	v_mfma_f32_16x16x32_bf16 v[58:61], v[162:165], v[186:189], v[58:61]
	v_mfma_f32_16x16x32_bf16 v[46:49], v[154:157], v[194:197], v[46:49]
	v_mfma_f32_16x16x32_bf16 v[42:45], v[162:165], v[194:197], v[42:45]
	v_mfma_f32_16x16x32_bf16 v[30:33], v[154:157], v[204:207], v[30:33]
	v_mfma_f32_16x16x32_bf16 v[26:29], v[162:165], v[204:207], v[26:29]
	v_mfma_f32_16x16x32_bf16 v[14:17], v[154:157], v[212:215], v[14:17]
	v_mfma_f32_16x16x32_bf16 v[10:13], v[162:165], v[212:215], v[10:13]
	v_mfma_f32_16x16x32_bf16 v[62:65], v[158:161], v[190:193], v[62:65]
	v_mfma_f32_16x16x32_bf16 v[58:61], v[166:169], v[190:193], v[58:61]
	v_mfma_f32_16x16x32_bf16 v[46:49], v[158:161], v[200:203], v[46:49]
	v_mfma_f32_16x16x32_bf16 v[42:45], v[166:169], v[200:203], v[42:45]
	v_mfma_f32_16x16x32_bf16 v[30:33], v[158:161], v[208:211], v[30:33]
	v_mfma_f32_16x16x32_bf16 v[26:29], v[166:169], v[208:211], v[26:29]
	v_mfma_f32_16x16x32_bf16 v[14:17], v[158:161], v[216:219], v[14:17]
	v_mfma_f32_16x16x32_bf16 v[10:13], v[166:169], v[216:219], v[10:13]
	v_mfma_f32_16x16x32_bf16 v[54:57], v[170:173], v[186:189], v[54:57]
	v_mfma_f32_16x16x32_bf16 v[50:53], v[178:181], v[186:189], v[50:53]
	v_mfma_f32_16x16x32_bf16 v[38:41], v[170:173], v[194:197], v[38:41]
	v_mfma_f32_16x16x32_bf16 v[34:37], v[178:181], v[194:197], v[34:37]
	v_mfma_f32_16x16x32_bf16 v[22:25], v[170:173], v[204:207], v[22:25]
	v_mfma_f32_16x16x32_bf16 v[18:21], v[178:181], v[204:207], v[18:21]
	v_mfma_f32_16x16x32_bf16 v[6:9], v[170:173], v[212:215], v[6:9]
	v_mfma_f32_16x16x32_bf16 v[2:5], v[178:181], v[212:215], v[2:5]
	v_mfma_f32_16x16x32_bf16 v[54:57], v[174:177], v[190:193], v[54:57]
	v_mfma_f32_16x16x32_bf16 v[50:53], v[182:185], v[190:193], v[50:53]
	v_mfma_f32_16x16x32_bf16 v[38:41], v[174:177], v[200:203], v[38:41]
	v_mfma_f32_16x16x32_bf16 v[34:37], v[182:185], v[200:203], v[34:37]
	v_mfma_f32_16x16x32_bf16 v[22:25], v[174:177], v[208:211], v[22:25]
	v_mfma_f32_16x16x32_bf16 v[18:21], v[182:185], v[208:211], v[18:21]
	v_mfma_f32_16x16x32_bf16 v[6:9], v[174:177], v[216:219], v[6:9]
	v_mfma_f32_16x16x32_bf16 v[2:5], v[182:185], v[216:219], v[2:5]
	s_barrier
; #define PG8_STAGE(bufoff, gbase, voff) do { _Pragma("unroll") for (int _i = 0; _i < 2; ++_i) \
;         __builtin_amdgcn_global_load_lds((const unsigned*)((const char*)(gbase) + (voff)[_i]), (PG8_LAS unsigned*)(lds + (bufoff) + ldsw + _i * 8192), 16, 0, 0); } while (0)
; #define PG8_LDA(dst, b, h) do { _Pragma("unroll") for (int m = 0; m < 4; ++m) _Pragma("unroll") for (int k = 0; k < 2; ++k) dst[m][k] = *(const PG8_LAS bf16x8*)(lds + PG8_SA(b, h) + aoff + m * 2048 + k * 1024); } while (0)
; #define PG8_LDB(dst, b, h) do { _Pragma("unroll") for (int n = 0; n < 2; ++n) _Pragma("unroll") for (int k = 0; k < 2; ++k) dst[n][k] = *(const PG8_LAS bf16x8*)(lds + PG8_SB(b, h) + boff + n * 2048 + k * 1024); } while (0)
; #define PG8_MMA(ai, bj, At, Bt) do { __builtin_amdgcn_s_setprio(1); _Pragma("unroll") for (int m = 0; m < 4; ++m) _Pragma("unroll") for (int n = 0; n < 2; ++n) _Pragma("unroll") for (int k = 0; k < 2; ++k) \
;         acc[ai][bj][m][n] = __builtin_amdgcn_mfma_f32_16x16x32_bf16(Bt[n][k], At[m][k], acc[ai][bj][m][n], 0, 0, 0); __builtin_amdgcn_s_setprio(0); } while (0)
; #define PG8_WAIT_V(n) asm volatile("s_waitcnt vmcnt(" #n ")" ::: "memory")
; #define PG8_WAIT_L(n) asm volatile("s_waitcnt lgkmcnt(" #n ")" ::: "memory")
; #define PG8_BAR __builtin_amdgcn_s_barrier()
; #define PG8_SCHED __builtin_amdgcn_sched_barrier(0)
; template <class Epi, class Sched, bool ALIGN_EPI = false, bool SP2 = false>
; __device__ __forceinline__ void gemm_phase(PG8_LAS unsigned char* lds, const Gemm g, const Sched& S, const Epi& E) {
;     ...
;             PG8_LDB(B0, 1, 0); PG8_LDB(B1, 1, 1); PG8_SCHED; PG8_LDA(At, 1, 0); PG8_STAGE(PG8_SA(0, 1), a2 + hstep, voffA);
;             PG8_WAIT_V(8); PG8_WAIT_L(0); PG8_BAR; PG8_MMA(0, 0, At, B0); PG8_MMA(0, 1, At, B1); PG8_BAR; PG8_SCHED;
;             PG8_LDA(At, 1, 1); PG8_STAGE(PG8_SB(1, 0), b3, voffB); PG8_STAGE(PG8_SB(1, 1), b3 + hstep, voffB); PG8_STAGE(PG8_SA(1, 0), a3, voffA);
;             PG8_WAIT_V(8); PG8_WAIT_L(0); PG8_BAR; PG8_MMA(1, 0, At, B0); PG8_MMA(1, 1, At, B1); PG8_BAR; PG8_SCHED;
	s_mov_b32 m0, s29
	s_nop 0
	global_load_lds_dwordx4 v136, s[36:37]
	s_mov_b32 m0, s40
	s_nop 0
	global_load_lds_dwordx4 v132, s[36:37]
	s_add_i32 s56, 0, 0x18000
	v_add_u32_e32 v153, s56, v148
	s_add_i32 s57, 0, 0x1c000
	ds_read_b128 v[154:157], v153
	ds_read_b128 v[158:161], v153 offset:1024
	ds_read_b128 v[162:165], v153 offset:2048
	ds_read_b128 v[166:169], v153 offset:3072
	v_add_u32_e32 v153, s57, v148
	ds_read_b128 v[170:173], v153
	ds_read_b128 v[174:177], v153 offset:1024
	ds_read_b128 v[178:181], v153 offset:2048
	ds_read_b128 v[182:185], v153 offset:3072
	s_add_u32 s36, s36, 0x100000
	s_addc_u32 s37, s37, 0
	s_mov_b32 m0, s41
	ds_read_b128 v[186:189], v152 offset:32768
	ds_read_b128 v[190:193], v152 offset:33792
	ds_read_b128 v[194:197], v152 offset:34816
	ds_read_b128 v[200:203], v152 offset:35840
	ds_read_b128 v[204:207], v152 offset:36864
	ds_read_b128 v[208:211], v152 offset:37888
	ds_read_b128 v[212:215], v152 offset:38912
	ds_read_b128 v[216:219], v152 offset:39936
	global_load_lds_dwordx4 v136, s[36:37]
	s_mov_b32 m0, s42
	s_nop 0
	global_load_lds_dwordx4 v132, s[36:37]
	s_waitcnt vmcnt(8)
	s_waitcnt lgkmcnt(0)
	s_barrier
	v_mfma_f32_16x16x32_bf16 v[126:129], v[154:157], v[186:189], v[126:129]
	v_mfma_f32_16x16x32_bf16 v[122:125], v[162:165], v[186:189], v[122:125]
	v_mfma_f32_16x16x32_bf16 v[110:113], v[154:157], v[194:197], v[110:113]
	v_mfma_f32_16x16x32_bf16 v[106:109], v[162:165], v[194:197], v[106:109]
	v_mfma_f32_16x16x32_bf16 v[94:97], v[154:157], v[204:207], v[94:97]
	v_mfma_f32_16x16x32_bf16 v[90:93], v[162:165], v[204:207], v[90:93]
	v_mfma_f32_16x16x32_bf16 v[78:81], v[154:157], v[212:215], v[78:81]
	v_mfma_f32_16x16x32_bf16 v[74:77], v[162:165], v[212:215], v[74:77]
	v_mfma_f32_16x16x32_bf16 v[126:129], v[158:161], v[190:193], v[126:129]
	v_mfma_f32_16x16x32_bf16 v[122:125], v[166:169], v[190:193], v[122:125]
	v_mfma_f32_16x16x32_bf16 v[110:113], v[158:161], v[200:203], v[110:113]
	v_mfma_f32_16x16x32_bf16 v[106:109], v[166:169], v[200:203], v[106:109]
	v_mfma_f32_16x16x32_bf16 v[94:97], v[158:161], v[208:211], v[94:97]
	v_mfma_f32_16x16x32_bf16 v[90:93], v[166:169], v[208:211], v[90:93]
	v_mfma_f32_16x16x32_bf16 v[78:81], v[158:161], v[216:219], v[78:81]
	v_mfma_f32_16x16x32_bf16 v[74:77], v[166:169], v[216:219], v[74:77]
	v_mfma_f32_16x16x32_bf16 v[118:121], v[170:173], v[186:189], v[118:121]
	v_mfma_f32_16x16x32_bf16 v[114:117], v[178:181], v[186:189], v[114:117]
	v_mfma_f32_16x16x32_bf16 v[102:105], v[170:173], v[194:197], v[102:105]
	v_mfma_f32_16x16x32_bf16 v[98:101], v[178:181], v[194:197], v[98:101]
	v_mfma_f32_16x16x32_bf16 v[86:89], v[170:173], v[204:207], v[86:89]
	v_mfma_f32_16x16x32_bf16 v[82:85], v[178:181], v[204:207], v[82:85]
	v_mfma_f32_16x16x32_bf16 v[70:73], v[170:173], v[212:215], v[70:73]
	v_mfma_f32_16x16x32_bf16 v[66:69], v[178:181], v[212:215], v[66:69]
	v_mfma_f32_16x16x32_bf16 v[118:121], v[174:177], v[190:193], v[118:121]
	v_mfma_f32_16x16x32_bf16 v[114:117], v[182:185], v[190:193], v[114:117]
	v_mfma_f32_16x16x32_bf16 v[102:105], v[174:177], v[200:203], v[102:105]
	v_mfma_f32_16x16x32_bf16 v[98:101], v[182:185], v[200:203], v[98:101]
	v_mfma_f32_16x16x32_bf16 v[86:89], v[174:177], v[208:211], v[86:89]
	v_mfma_f32_16x16x32_bf16 v[82:85], v[182:185], v[208:211], v[82:85]
	v_mfma_f32_16x16x32_bf16 v[70:73], v[174:177], v[216:219], v[70:73]
	v_mfma_f32_16x16x32_bf16 v[66:69], v[182:185], v[216:219], v[66:69]
	s_barrier
	s_add_i32 s36, s56, s33
	v_lshl_add_u64 v[146:147], v[146:147], 0, s[8:9]
	s_mov_b32 m0, s36
	ds_read_b128 v[186:189], v152 offset:49152
	ds_read_b128 v[190:193], v152 offset:50176
	ds_read_b128 v[194:197], v152 offset:51200
	ds_read_b128 v[200:203], v152 offset:52224
	ds_read_b128 v[204:207], v152 offset:53248
	ds_read_b128 v[208:211], v152 offset:54272
	ds_read_b128 v[212:215], v152 offset:55296
	ds_read_b128 v[216:219], v152 offset:56320
	global_load_lds_dwordx4 v[146:147], off
	s_add_i32 m0, s36, 0x2000
	s_add_u32 s34, s34, 0x100080
	v_lshl_add_u64 v[146:147], v[220:221], 0, s[8:9]
	s_addc_u32 s35, s35, 0
	s_add_i32 s36, s57, s33
	global_load_lds_dwordx4 v[146:147], off
	s_mov_b32 m0, s36
	s_nop 0
	global_load_lds_dwordx4 v134, s[34:35]
	s_add_i32 m0, s36, 0x2000
	s_nop 0
	global_load_lds_dwordx4 v130, s[34:35]
	s_waitcnt vmcnt(6)
	s_waitcnt lgkmcnt(0)
	s_barrier
	v_mfma_f32_16x16x32_bf16 v[62:65], v[154:157], v[186:189], v[62:65]
	v_mfma_f32_16x16x32_bf16 v[58:61], v[162:165], v[186:189], v[58:61]
	v_mfma_f32_16x16x32_bf16 v[46:49], v[154:157], v[194:197], v[46:49]
	v_mfma_f32_16x16x32_bf16 v[42:45], v[162:165], v[194:197], v[42:45]
	v_mfma_f32_16x16x32_bf16 v[30:33], v[154:157], v[204:207], v[30:33]
	v_mfma_f32_16x16x32_bf16 v[26:29], v[162:165], v[204:207], v[26:29]
	v_mfma_f32_16x16x32_bf16 v[14:17], v[154:157], v[212:215], v[14:17]
	v_mfma_f32_16x16x32_bf16 v[10:13], v[162:165], v[212:215], v[10:13]
	v_mfma_f32_16x16x32_bf16 v[62:65], v[158:161], v[190:193], v[62:65]
	v_mfma_f32_16x16x32_bf16 v[58:61], v[166:169], v[190:193], v[58:61]
	v_mfma_f32_16x16x32_bf16 v[46:49], v[158:161], v[200:203], v[46:49]
	v_mfma_f32_16x16x32_bf16 v[42:45], v[166:169], v[200:203], v[42:45]
	v_mfma_f32_16x16x32_bf16 v[30:33], v[158:161], v[208:211], v[30:33]
	v_mfma_f32_16x16x32_bf16 v[26:29], v[166:169], v[208:211], v[26:29]
	v_mfma_f32_16x16x32_bf16 v[14:17], v[158:161], v[216:219], v[14:17]
	v_mfma_f32_16x16x32_bf16 v[10:13], v[166:169], v[216:219], v[10:13]
	v_mfma_f32_16x16x32_bf16 v[54:57], v[170:173], v[186:189], v[54:57]
	v_mfma_f32_16x16x32_bf16 v[50:53], v[178:181], v[186:189], v[50:53]
	v_mfma_f32_16x16x32_bf16 v[38:41], v[170:173], v[194:197], v[38:41]
	v_mfma_f32_16x16x32_bf16 v[34:37], v[178:181], v[194:197], v[34:37]
	v_mfma_f32_16x16x32_bf16 v[22:25], v[170:173], v[204:207], v[22:25]
	v_mfma_f32_16x16x32_bf16 v[18:21], v[178:181], v[204:207], v[18:21]
	v_mfma_f32_16x16x32_bf16 v[6:9], v[170:173], v[212:215], v[6:9]
	v_mfma_f32_16x16x32_bf16 v[2:5], v[178:181], v[212:215], v[2:5]
	v_mfma_f32_16x16x32_bf16 v[54:57], v[174:177], v[190:193], v[54:57]
	v_mfma_f32_16x16x32_bf16 v[50:53], v[182:185], v[190:193], v[50:53]
	v_mfma_f32_16x16x32_bf16 v[38:41], v[174:177], v[200:203], v[38:41]
	v_mfma_f32_16x16x32_bf16 v[34:37], v[182:185], v[200:203], v[34:37]
	v_mfma_f32_16x16x32_bf16 v[22:25], v[174:177], v[208:211], v[22:25]
	v_mfma_f32_16x16x32_bf16 v[18:21], v[182:185], v[208:211], v[18:21]
	v_mfma_f32_16x16x32_bf16 v[6:9], v[174:177], v[216:219], v[6:9]
	v_mfma_f32_16x16x32_bf16 v[2:5], v[182:185], v[216:219], v[2:5]
	s_barrier
	s_add_i32 s55, s55, 2
	s_add_u32 s30, s30, 0x100
	s_addc_u32 s31, s31, 0
	s_add_u32 s53, s53, 0x100
	s_addc_u32 s54, s54, 0
	s_cmp_gt_u32 s55, 61
	s_cbranch_scc0 .LBB0_1081
	s_and_b64 vcc, exec, s[10:11]
	s_cbranch_vccz .LBB0_1084
	s_barrier

; #define PG8_STAGE(bufoff, gbase, voff) do { _Pragma("unroll") for (int _i = 0; _i < 2; ++_i) \
;         __builtin_amdgcn_global_load_lds((const unsigned*)((const char*)(gbase) + (voff)[_i]), (PG8_LAS unsigned*)(lds + (bufoff) + ldsw + _i * 8192), 16, 0, 0); } while (0)
; #define PG8_LDA(dst, b, h) do { _Pragma("unroll") for (int m = 0; m < 4; ++m) _Pragma("unroll") for (int k = 0; k < 2; ++k) dst[m][k] = *(const PG8_LAS bf16x8*)(lds + PG8_SA(b, h) + aoff + m * 2048 + k * 1024); } while (0)
; #define PG8_LDB(dst, b, h) do { _Pragma("unroll") for (int n = 0; n < 2; ++n) _Pragma("unroll") for (int k = 0; k < 2; ++k) dst[n][k] = *(const PG8_LAS bf16x8*)(lds + PG8_SB(b, h) + boff + n * 2048 + k * 1024); } while (0)
; #define PG8_MMA(ai, bj, At, Bt) do { __builtin_amdgcn_s_setprio(1); _Pragma("unroll") for (int m = 0; m < 4; ++m) _Pragma("unroll") for (int n = 0; n < 2; ++n) _Pragma("unroll") for (int k = 0; k < 2; ++k) \
;         acc[ai][bj][m][n] = __builtin_amdgcn_mfma_f32_16x16x32_bf16(Bt[n][k], At[m][k], acc[ai][bj][m][n], 0, 0, 0); __builtin_amdgcn_s_setprio(0); } while (0)
; #define PG8_WAIT_V(n) asm volatile("s_waitcnt vmcnt(" #n ")" ::: "memory")
; #define PG8_BAR __builtin_amdgcn_s_barrier()
; template <class Epi, class Sched, bool ALIGN_EPI = false, bool SP2 = false>
; __device__ __forceinline__ void gemm_phase(PG8_LAS unsigned char* lds, const Gemm g, const Sched& S, const Epi& E) {
;     ...
;         for (int t = 0; t < nt; t += 2) {
;             const bool last = (t == nt - 2);
;             const char* a1 = cA + (size_t)(t + 1) * kstep;
;             const char* a2 = last ? nA : cA + (size_t)(t + 2) * kstep; const char* b2 = last ? nB : cB + (size_t)(t + 2) * kstep;
;             const char* a3 = a2 + kstep; const char* b3 = b2 + kstep;
;             if (last && has_next) S.a_ready(nxt);
;             if constexpr (SP2) {
;             PG8_LDB(B0, 0, 0); PG8_LDB(B1, 0, 1); PG8_SCHED; PG8_LDA(At, 0, 0); PG8_STAGE(PG8_SA(1, 1), a1 + hstep, voffA);
;             PG8_WAIT_V(8); PG8_WAIT_L(0); PG8_BAR; PG8_MMA(0, 0, At, B0); PG8_MMA(0, 1, At, B1); PG8_BAR; PG8_SCHED;
;             PG8_LDA(At, 0, 1); PG8_STAGE(PG8_SB(0, 0), b2, voffB); PG8_STAGE(PG8_SB(0, 1), b2 + hstep, voffB); PG8_STAGE(PG8_SA(0, 0), a2, voffA);
;             PG8_WAIT_V(8); PG8_WAIT_L(0); PG8_BAR; PG8_MMA(1, 0, At, B0); PG8_MMA(1, 1, At, B1); PG8_BAR; PG8_SCHED;
.LBB0_1164:
	s_add_u32 s16, s14, 0xffd50000
	s_addc_u32 s17, s15, -1
	s_mov_b32 m0, s29
	s_nop 0
	global_load_lds_dwordx4 v128, s[16:17]
	s_mov_b32 m0, s30
	s_nop 0
	global_load_lds_dwordx4 v130, s[16:17]
	s_add_u32 s16, s16, 0x80
	s_addc_u32 s17, s17, 0
	ds_read_b128 v[140:143], v193
	ds_read_b128 v[144:147], v193 offset:1024
	ds_read_b128 v[148:151], v193 offset:2048
	ds_read_b128 v[152:155], v193 offset:3072
	ds_read_b128 v[156:159], v194
	ds_read_b128 v[160:163], v194 offset:1024
	ds_read_b128 v[164:167], v194 offset:2048
	ds_read_b128 v[168:171], v194 offset:3072
	s_cmpk_eq_i32 s41, 0xa8
	s_cselect_b32 s21, s5, s17
	s_cselect_b32 s20, s4, s16
	s_cselect_b32 s17, s13, s40
	s_cselect_b32 s16, s12, s39
	s_add_i32 m0, s24, 0xc000
	ds_read_b128 v[172:175], v195
	ds_read_b128 v[176:179], v195 offset:1024
	ds_read_b128 v[180:183], v195 offset:2048
	ds_read_b128 v[184:187], v195 offset:3072
	ds_read_b128 v[196:199], v195 offset:4096
	ds_read_b128 v[200:203], v195 offset:5120
	ds_read_b128 v[204:207], v195 offset:6144
	ds_read_b128 v[208:211], v195 offset:7168
	global_load_lds_dwordx4 v132, s[14:15]
	s_add_i32 m0, s24, 0xe000
	s_nop 0
	global_load_lds_dwordx4 v134, s[14:15]
	s_waitcnt vmcnt(8)
	s_waitcnt lgkmcnt(0)
	s_barrier
	v_mfma_f32_16x16x32_bf16 v[124:127], v[140:143], v[172:175], v[124:127]
	v_mfma_f32_16x16x32_bf16 v[120:123], v[148:151], v[172:175], v[120:123]
	v_mfma_f32_16x16x32_bf16 v[112:115], v[140:143], v[180:183], v[112:115]
	v_mfma_f32_16x16x32_bf16 v[104:107], v[148:151], v[180:183], v[104:107]
	v_mfma_f32_16x16x32_bf16 v[96:99], v[140:143], v[196:199], v[96:99]
	v_mfma_f32_16x16x32_bf16 v[88:91], v[148:151], v[196:199], v[88:91]
	v_mfma_f32_16x16x32_bf16 v[80:83], v[140:143], v[204:207], v[80:83]
	v_mfma_f32_16x16x32_bf16 v[72:75], v[148:151], v[204:207], v[72:75]
	v_mfma_f32_16x16x32_bf16 v[124:127], v[144:147], v[176:179], v[124:127]
	v_mfma_f32_16x16x32_bf16 v[120:123], v[152:155], v[176:179], v[120:123]
	v_mfma_f32_16x16x32_bf16 v[112:115], v[144:147], v[184:187], v[112:115]
	v_mfma_f32_16x16x32_bf16 v[104:107], v[152:155], v[184:187], v[104:107]
	v_mfma_f32_16x16x32_bf16 v[96:99], v[144:147], v[200:203], v[96:99]
	v_mfma_f32_16x16x32_bf16 v[88:91], v[152:155], v[200:203], v[88:91]
	v_mfma_f32_16x16x32_bf16 v[80:83], v[144:147], v[208:211], v[80:83]
	v_mfma_f32_16x16x32_bf16 v[72:75], v[152:155], v[208:211], v[72:75]
	v_mfma_f32_16x16x32_bf16 v[116:119], v[156:159], v[172:175], v[116:119]
	v_mfma_f32_16x16x32_bf16 v[108:111], v[164:167], v[172:175], v[108:111]
	v_mfma_f32_16x16x32_bf16 v[100:103], v[156:159], v[180:183], v[100:103]
	v_mfma_f32_16x16x32_bf16 v[92:95], v[164:167], v[180:183], v[92:95]
	v_mfma_f32_16x16x32_bf16 v[84:87], v[156:159], v[196:199], v[84:87]
	v_mfma_f32_16x16x32_bf16 v[76:79], v[164:167], v[196:199], v[76:79]
	v_mfma_f32_16x16x32_bf16 v[68:71], v[156:159], v[204:207], v[68:71]
	v_mfma_f32_16x16x32_bf16 v[64:67], v[164:167], v[204:207], v[64:67]
	v_mfma_f32_16x16x32_bf16 v[116:119], v[160:163], v[176:179], v[116:119]
	v_mfma_f32_16x16x32_bf16 v[108:111], v[168:171], v[176:179], v[108:111]
	v_mfma_f32_16x16x32_bf16 v[100:103], v[160:163], v[184:187], v[100:103]
	v_mfma_f32_16x16x32_bf16 v[92:95], v[168:171], v[184:187], v[92:95]
	v_mfma_f32_16x16x32_bf16 v[84:87], v[160:163], v[200:203], v[84:87]
	v_mfma_f32_16x16x32_bf16 v[76:79], v[168:171], v[200:203], v[76:79]
	v_mfma_f32_16x16x32_bf16 v[68:71], v[160:163], v[208:211], v[68:71]
	v_mfma_f32_16x16x32_bf16 v[64:67], v[168:171], v[208:211], v[64:67]
	s_barrier
	s_add_i32 s42, s33, s23
	v_lshl_add_u64 v[188:189], s[16:17], 0, v[128:129]
	s_mov_b32 m0, s42
	ds_read_b128 v[172:175], v195 offset:16384
	ds_read_b128 v[176:179], v195 offset:17408
	ds_read_b128 v[180:183], v195 offset:18432
	ds_read_b128 v[184:187], v195 offset:19456
	ds_read_b128 v[196:199], v195 offset:20480
	ds_read_b128 v[200:203], v195 offset:21504
	ds_read_b128 v[204:207], v195 offset:22528
	ds_read_b128 v[208:211], v195 offset:23552
	global_load_lds_dwordx4 v128, s[16:17]
	s_add_i32 m0, s42, 0x2000
	s_add_u32 s42, s16, 0x2b0000
	v_lshl_add_u64 v[212:213], s[16:17], 0, v[130:131]
	s_addc_u32 s43, s17, 0
	s_add_i32 s44, s34, s23
	global_load_lds_dwordx4 v130, s[16:17]
	s_mov_b32 m0, s44
	s_nop 0
	global_load_lds_dwordx4 v128, s[42:43]
	s_add_i32 m0, s44, 0x2000
	s_nop 0
	global_load_lds_dwordx4 v130, s[42:43]
	s_waitcnt vmcnt(6)
	s_waitcnt lgkmcnt(0)
	s_barrier
	v_mfma_f32_16x16x32_bf16 v[60:63], v[140:143], v[172:175], v[60:63]
	v_mfma_f32_16x16x32_bf16 v[56:59], v[148:151], v[172:175], v[56:59]
	v_mfma_f32_16x16x32_bf16 v[48:51], v[140:143], v[180:183], v[48:51]
	v_mfma_f32_16x16x32_bf16 v[40:43], v[148:151], v[180:183], v[40:43]
	v_mfma_f32_16x16x32_bf16 v[32:35], v[140:143], v[196:199], v[32:35]
	v_mfma_f32_16x16x32_bf16 v[24:27], v[148:151], v[196:199], v[24:27]
	v_mfma_f32_16x16x32_bf16 v[16:19], v[140:143], v[204:207], v[16:19]
	v_mfma_f32_16x16x32_bf16 v[8:11], v[148:151], v[204:207], v[8:11]
	v_mfma_f32_16x16x32_bf16 v[60:63], v[144:147], v[176:179], v[60:63]
	v_mfma_f32_16x16x32_bf16 v[56:59], v[152:155], v[176:179], v[56:59]
	v_mfma_f32_16x16x32_bf16 v[48:51], v[144:147], v[184:187], v[48:51]
	v_mfma_f32_16x16x32_bf16 v[40:43], v[152:155], v[184:187], v[40:43]
	v_mfma_f32_16x16x32_bf16 v[32:35], v[144:147], v[200:203], v[32:35]
	v_mfma_f32_16x16x32_bf16 v[24:27], v[152:155], v[200:203], v[24:27]
	v_mfma_f32_16x16x32_bf16 v[16:19], v[144:147], v[208:211], v[16:19]
	v_mfma_f32_16x16x32_bf16 v[8:11], v[152:155], v[208:211], v[8:11]
	v_mfma_f32_16x16x32_bf16 v[52:55], v[156:159], v[172:175], v[52:55]
	v_mfma_f32_16x16x32_bf16 v[44:47], v[164:167], v[172:175], v[44:47]
	v_mfma_f32_16x16x32_bf16 v[36:39], v[156:159], v[180:183], v[36:39]
	v_mfma_f32_16x16x32_bf16 v[28:31], v[164:167], v[180:183], v[28:31]
	v_mfma_f32_16x16x32_bf16 v[20:23], v[156:159], v[196:199], v[20:23]
	v_mfma_f32_16x16x32_bf16 v[12:15], v[164:167], v[196:199], v[12:15]
	v_mfma_f32_16x16x32_bf16 v[4:7], v[156:159], v[204:207], v[4:7]
	v_mfma_f32_16x16x32_bf16 v[0:3], v[164:167], v[204:207], v[0:3]
	v_mfma_f32_16x16x32_bf16 v[52:55], v[160:163], v[176:179], v[52:55]
	v_mfma_f32_16x16x32_bf16 v[44:47], v[168:171], v[176:179], v[44:47]
	v_mfma_f32_16x16x32_bf16 v[36:39], v[160:163], v[184:187], v[36:39]
	v_mfma_f32_16x16x32_bf16 v[28:31], v[168:171], v[184:187], v[28:31]
	v_mfma_f32_16x16x32_bf16 v[20:23], v[160:163], v[200:203], v[20:23]
	v_mfma_f32_16x16x32_bf16 v[12:15], v[168:171], v[200:203], v[12:15]
	v_mfma_f32_16x16x32_bf16 v[4:7], v[160:163], v[208:211], v[4:7]
	v_mfma_f32_16x16x32_bf16 v[0:3], v[168:171], v[208:211], v[0:3]
	s_barrier
; #define PG8_STAGE(bufoff, gbase, voff) do { _Pragma("unroll") for (int _i = 0; _i < 2; ++_i) \
;         __builtin_amdgcn_global_load_lds((const unsigned*)((const char*)(gbase) + (voff)[_i]), (PG8_LAS unsigned*)(lds + (bufoff) + ldsw + _i * 8192), 16, 0, 0); } while (0)
; #define PG8_LDA(dst, b, h) do { _Pragma("unroll") for (int m = 0; m < 4; ++m) _Pragma("unroll") for (int k = 0; k < 2; ++k) dst[m][k] = *(const PG8_LAS bf16x8*)(lds + PG8_SA(b, h) + aoff + m * 2048 + k * 1024); } while (0)
; #define PG8_LDB(dst, b, h) do { _Pragma("unroll") for (int n = 0; n < 2; ++n) _Pragma("unroll") for (int k = 0; k < 2; ++k) dst[n][k] = *(const PG8_LAS bf16x8*)(lds + PG8_SB(b, h) + boff + n * 2048 + k * 1024); } while (0)
; #define PG8_MMA(ai, bj, At, Bt) do { __builtin_amdgcn_s_setprio(1); _Pragma("unroll") for (int m = 0; m < 4; ++m) _Pragma("unroll") for (int n = 0; n < 2; ++n) _Pragma("unroll") for (int k = 0; k < 2; ++k) \
;         acc[ai][bj][m][n] = __builtin_amdgcn_mfma_f32_16x16x32_bf16(Bt[n][k], At[m][k], acc[ai][bj][m][n], 0, 0, 0); __builtin_amdgcn_s_setprio(0); } while (0)
; #define PG8_WAIT_V(n) asm volatile("s_waitcnt vmcnt(" #n ")" ::: "memory")
; #define PG8_WAIT_L(n) asm volatile("s_waitcnt lgkmcnt(" #n ")" ::: "memory")
; #define PG8_BAR __builtin_amdgcn_s_barrier()
; #define PG8_SCHED __builtin_amdgcn_sched_barrier(0)
; template <class Epi, class Sched, bool ALIGN_EPI = false, bool SP2 = false>
; __device__ __forceinline__ void gemm_phase(PG8_LAS unsigned char* lds, const Gemm g, const Sched& S, const Epi& E) {
;     ...
;             PG8_LDB(B0, 1, 0); PG8_LDB(B1, 1, 1); PG8_SCHED; PG8_LDA(At, 1, 0); PG8_STAGE(PG8_SA(0, 1), a2 + hstep, voffA);
;             PG8_WAIT_V(8); PG8_WAIT_L(0); PG8_BAR; PG8_MMA(0, 0, At, B0); PG8_MMA(0, 1, At, B1); PG8_BAR; PG8_SCHED;
;             PG8_LDA(At, 1, 1); PG8_STAGE(PG8_SB(1, 0), b3, voffB); PG8_STAGE(PG8_SB(1, 1), b3 + hstep, voffB); PG8_STAGE(PG8_SA(1, 0), a3, voffA);
;             PG8_WAIT_V(8); PG8_WAIT_L(0); PG8_BAR; PG8_MMA(1, 0, At, B0); PG8_MMA(1, 1, At, B1); PG8_BAR; PG8_SCHED;
	s_mov_b32 m0, s24
	s_nop 0
	global_load_lds_dwordx4 v128, s[20:21]
	s_mov_b32 m0, s25
	s_nop 0
	global_load_lds_dwordx4 v130, s[20:21]
	s_add_i32 s42, 0, 0x18000
	s_add_i32 s43, 0, 0x1c000
	v_add_u32_e32 v152, s42, v191
	v_add_u32_e32 v168, s43, v191
	ds_read_b128 v[140:143], v152
	ds_read_b128 v[144:147], v152 offset:1024
	ds_read_b128 v[148:151], v152 offset:2048
	ds_read_b128 v[152:155], v152 offset:3072
	ds_read_b128 v[156:159], v168
	ds_read_b128 v[160:163], v168 offset:1024
	ds_read_b128 v[164:167], v168 offset:2048
	ds_read_b128 v[168:171], v168 offset:3072
	s_add_u32 s20, s20, 0x2b0000
	s_addc_u32 s21, s21, 0
	s_mov_b32 m0, s26
	ds_read_b128 v[172:175], v195 offset:32768
	ds_read_b128 v[176:179], v195 offset:33792
	ds_read_b128 v[180:183], v195 offset:34816
	ds_read_b128 v[184:187], v195 offset:35840
	ds_read_b128 v[196:199], v195 offset:36864
	ds_read_b128 v[200:203], v195 offset:37888
	ds_read_b128 v[204:207], v195 offset:38912
	ds_read_b128 v[208:211], v195 offset:39936
	global_load_lds_dwordx4 v128, s[20:21]
	s_mov_b32 m0, s27
	s_nop 0
	global_load_lds_dwordx4 v130, s[20:21]
	s_waitcnt vmcnt(8)
	s_waitcnt lgkmcnt(0)
	s_barrier
	v_mfma_f32_16x16x32_bf16 v[124:127], v[140:143], v[172:175], v[124:127]
	v_mfma_f32_16x16x32_bf16 v[120:123], v[148:151], v[172:175], v[120:123]
	v_mfma_f32_16x16x32_bf16 v[112:115], v[140:143], v[180:183], v[112:115]
	v_mfma_f32_16x16x32_bf16 v[104:107], v[148:151], v[180:183], v[104:107]
	v_mfma_f32_16x16x32_bf16 v[96:99], v[140:143], v[196:199], v[96:99]
	v_mfma_f32_16x16x32_bf16 v[88:91], v[148:151], v[196:199], v[88:91]
	v_mfma_f32_16x16x32_bf16 v[80:83], v[140:143], v[204:207], v[80:83]
	v_mfma_f32_16x16x32_bf16 v[72:75], v[148:151], v[204:207], v[72:75]
	v_mfma_f32_16x16x32_bf16 v[124:127], v[144:147], v[176:179], v[124:127]
	v_mfma_f32_16x16x32_bf16 v[120:123], v[152:155], v[176:179], v[120:123]
	v_mfma_f32_16x16x32_bf16 v[112:115], v[144:147], v[184:187], v[112:115]
	v_mfma_f32_16x16x32_bf16 v[104:107], v[152:155], v[184:187], v[104:107]
	v_mfma_f32_16x16x32_bf16 v[96:99], v[144:147], v[200:203], v[96:99]
	v_mfma_f32_16x16x32_bf16 v[88:91], v[152:155], v[200:203], v[88:91]
	v_mfma_f32_16x16x32_bf16 v[80:83], v[144:147], v[208:211], v[80:83]
	v_mfma_f32_16x16x32_bf16 v[72:75], v[152:155], v[208:211], v[72:75]
	v_mfma_f32_16x16x32_bf16 v[116:119], v[156:159], v[172:175], v[116:119]
	v_mfma_f32_16x16x32_bf16 v[108:111], v[164:167], v[172:175], v[108:111]
	v_mfma_f32_16x16x32_bf16 v[100:103], v[156:159], v[180:183], v[100:103]
	v_mfma_f32_16x16x32_bf16 v[92:95], v[164:167], v[180:183], v[92:95]
	v_mfma_f32_16x16x32_bf16 v[84:87], v[156:159], v[196:199], v[84:87]
	v_mfma_f32_16x16x32_bf16 v[76:79], v[164:167], v[196:199], v[76:79]
	v_mfma_f32_16x16x32_bf16 v[68:71], v[156:159], v[204:207], v[68:71]
	v_mfma_f32_16x16x32_bf16 v[64:67], v[164:167], v[204:207], v[64:67]
	v_mfma_f32_16x16x32_bf16 v[116:119], v[160:163], v[176:179], v[116:119]
	v_mfma_f32_16x16x32_bf16 v[108:111], v[168:171], v[176:179], v[108:111]
	v_mfma_f32_16x16x32_bf16 v[100:103], v[160:163], v[184:187], v[100:103]
	v_mfma_f32_16x16x32_bf16 v[92:95], v[168:171], v[184:187], v[92:95]
	v_mfma_f32_16x16x32_bf16 v[84:87], v[160:163], v[200:203], v[84:87]
	v_mfma_f32_16x16x32_bf16 v[76:79], v[168:171], v[200:203], v[76:79]
	v_mfma_f32_16x16x32_bf16 v[68:71], v[160:163], v[208:211], v[68:71]
	v_mfma_f32_16x16x32_bf16 v[64:67], v[168:171], v[208:211], v[64:67]
	s_barrier
	s_add_i32 s20, s42, s23
	v_lshl_add_u64 v[188:189], v[188:189], 0, s[8:9]
	s_mov_b32 m0, s20
	ds_read_b128 v[172:175], v195 offset:49152
	ds_read_b128 v[176:179], v195 offset:50176
	ds_read_b128 v[180:183], v195 offset:51200
	ds_read_b128 v[184:187], v195 offset:52224
	ds_read_b128 v[196:199], v195 offset:53248
	ds_read_b128 v[200:203], v195 offset:54272
	ds_read_b128 v[204:207], v195 offset:55296
	ds_read_b128 v[208:211], v195 offset:56320
	global_load_lds_dwordx4 v[188:189], off
	s_add_i32 m0, s20, 0x2000
	s_add_u32 s16, s16, 0x2b0080
	v_lshl_add_u64 v[188:189], v[212:213], 0, s[8:9]
	s_addc_u32 s17, s17, 0
	s_add_i32 s20, s43, s23
	global_load_lds_dwordx4 v[188:189], off
	s_mov_b32 m0, s20
	s_nop 0
	global_load_lds_dwordx4 v128, s[16:17]
	s_add_i32 m0, s20, 0x2000
	s_nop 0
	global_load_lds_dwordx4 v130, s[16:17]
	s_waitcnt vmcnt(6)
	s_waitcnt lgkmcnt(0)
	s_barrier
	v_mfma_f32_16x16x32_bf16 v[60:63], v[140:143], v[172:175], v[60:63]
	v_mfma_f32_16x16x32_bf16 v[56:59], v[148:151], v[172:175], v[56:59]
	v_mfma_f32_16x16x32_bf16 v[48:51], v[140:143], v[180:183], v[48:51]
	v_mfma_f32_16x16x32_bf16 v[40:43], v[148:151], v[180:183], v[40:43]
	v_mfma_f32_16x16x32_bf16 v[32:35], v[140:143], v[196:199], v[32:35]
	v_mfma_f32_16x16x32_bf16 v[24:27], v[148:151], v[196:199], v[24:27]
	v_mfma_f32_16x16x32_bf16 v[16:19], v[140:143], v[204:207], v[16:19]
	v_mfma_f32_16x16x32_bf16 v[8:11], v[148:151], v[204:207], v[8:11]
	v_mfma_f32_16x16x32_bf16 v[60:63], v[144:147], v[176:179], v[60:63]
	v_mfma_f32_16x16x32_bf16 v[56:59], v[152:155], v[176:179], v[56:59]
	v_mfma_f32_16x16x32_bf16 v[48:51], v[144:147], v[184:187], v[48:51]
	v_mfma_f32_16x16x32_bf16 v[40:43], v[152:155], v[184:187], v[40:43]
	v_mfma_f32_16x16x32_bf16 v[32:35], v[144:147], v[200:203], v[32:35]
	v_mfma_f32_16x16x32_bf16 v[24:27], v[152:155], v[200:203], v[24:27]
	v_mfma_f32_16x16x32_bf16 v[16:19], v[144:147], v[208:211], v[16:19]
	v_mfma_f32_16x16x32_bf16 v[8:11], v[152:155], v[208:211], v[8:11]
	v_mfma_f32_16x16x32_bf16 v[52:55], v[156:159], v[172:175], v[52:55]
	v_mfma_f32_16x16x32_bf16 v[44:47], v[164:167], v[172:175], v[44:47]
	v_mfma_f32_16x16x32_bf16 v[36:39], v[156:159], v[180:183], v[36:39]
	v_mfma_f32_16x16x32_bf16 v[28:31], v[164:167], v[180:183], v[28:31]
	v_mfma_f32_16x16x32_bf16 v[20:23], v[156:159], v[196:199], v[20:23]
	v_mfma_f32_16x16x32_bf16 v[12:15], v[164:167], v[196:199], v[12:15]
	v_mfma_f32_16x16x32_bf16 v[4:7], v[156:159], v[204:207], v[4:7]
	v_mfma_f32_16x16x32_bf16 v[0:3], v[164:167], v[204:207], v[0:3]
	v_mfma_f32_16x16x32_bf16 v[52:55], v[160:163], v[176:179], v[52:55]
	v_mfma_f32_16x16x32_bf16 v[44:47], v[168:171], v[176:179], v[44:47]
	v_mfma_f32_16x16x32_bf16 v[36:39], v[160:163], v[184:187], v[36:39]
	v_mfma_f32_16x16x32_bf16 v[28:31], v[168:171], v[184:187], v[28:31]
	v_mfma_f32_16x16x32_bf16 v[20:23], v[160:163], v[200:203], v[20:23]
	v_mfma_f32_16x16x32_bf16 v[12:15], v[168:171], v[200:203], v[12:15]
	v_mfma_f32_16x16x32_bf16 v[4:7], v[160:163], v[208:211], v[4:7]
	v_mfma_f32_16x16x32_bf16 v[0:3], v[168:171], v[208:211], v[0:3]
	s_barrier
	s_add_i32 s41, s41, 2
	s_add_u32 s14, s14, 0x100
	s_addc_u32 s15, s15, 0
	s_add_u32 s39, s39, 0x100
	s_addc_u32 s40, s40, 0
	s_cmpk_gt_u32 s41, 0xa9
	s_cbranch_scc0 .LBB0_1164
	s_and_b64 vcc, exec, s[10:11]
	s_cbranch_vccz .LBB0_1167
	s_barrier
